# FNet fold: 1024 scalar f32 FMAs per k-chunk replaced by 512 v_pk_fma_f32 with op_sel broadcast of the row weight (packed f32 instruction selection in the VALU-bound prep loop)
# speedup vs baseline: 1.0001x; 1.0001x over previous
; #define LAS __attribute__((address_space(3)))
; __device__ __forceinline__ void phase_prep(const Params& p, LAS unsigned char* lds) {
;     ...
;             for (int kci = 0; kci < 4; ++kci) { const int kc = kc4 * 4 + kci; asm volatile("" ::: "memory");
;             const int k = kc * 128 + (tid & 127), eg = tid >> 7;
;             const float* row = p.w_in + ((size_t)l * DM + k) * INW + ZW + g * 64;
;             float a[16];
; #pragma unroll
;             for (int j = 0; j < 16; ++j) a[j] = 0.f;
;             f32x4 rw[16];
; #pragma unroll
;             for (int c4 = 0; c4 < 16; ++c4) rw[c4] = *(const f32x4*)(row + 4 * c4);
; #pragma unroll
;             for (int c4 = 0; c4 < 16; ++c4)
; #pragma unroll
;                 for (int cc = 0; cc < 4; ++cc) { const float wv = rw[c4][cc]; const LAS f32x4* mp = (const LAS f32x4*)(Mf + (4 * c4 + cc) * 64 + eg * 16);
; #pragma unroll
;                     for (int j4 = 0; j4 < 4; ++j4) { const f32x4 mv = mp[j4]; a[4 * j4 + 0] += wv * mv[0]; a[4 * j4 + 1] += wv * mv[1]; a[4 * j4 + 2] += wv * mv[2]; a[4 * j4 + 3] += wv * mv[3]; } }
.LBB0_581:
	global_load_dwordx4 v[48:51], v[62:63], off offset:-80
	global_load_dwordx4 v[52:55], v[62:63], off offset:-96
	global_load_dwordx4 v[86:89], v[62:63], off offset:-112
	global_load_dwordx4 v[90:93], v[62:63], off offset:-128
	global_load_dwordx4 v[32:35], v[62:63], off offset:-16
	global_load_dwordx4 v[36:39], v[62:63], off offset:-32
	global_load_dwordx4 v[40:43], v[62:63], off offset:-48
	global_load_dwordx4 v[44:47], v[62:63], off offset:-64
	global_load_dwordx4 v[16:19], v[62:63], off offset:48
	global_load_dwordx4 v[20:23], v[62:63], off offset:32
	global_load_dwordx4 v[24:27], v[62:63], off offset:16
	global_load_dwordx4 v[28:31], v[62:63], off
	global_load_dwordx4 v[0:3], v[62:63], off offset:112
	global_load_dwordx4 v[4:7], v[62:63], off offset:96
	global_load_dwordx4 v[8:11], v[62:63], off offset:80
	global_load_dwordx4 v[12:15], v[62:63], off offset:64
	s_mov_b32 s2, 0x4001000
	ds_read_b128 v[102:105], v66 offset:1024
	ds_read_b128 v[106:109], v66 offset:1040
	ds_read_b128 v[110:113], v66 offset:1056
	ds_read_b128 v[114:117], v66 offset:1072
	ds_read_b128 v[118:121], v66 offset:1280
	ds_read_b128 v[122:125], v66 offset:1296
	ds_read_b128 v[126:129], v66 offset:1312
	ds_read_b128 v[130:133], v66 offset:1328
	ds_read_b128 v[134:137], v66 offset:1536
	ds_read_b128 v[138:141], v66 offset:1552
	ds_read_b128 v[142:145], v66 offset:1568
	ds_read_b128 v[146:149], v66 offset:1584
	ds_read_b128 v[150:153], v66 offset:1792
	ds_read_b128 v[158:161], v66 offset:1808
	ds_read_b128 v[162:165], v66 offset:1824
	ds_read_b128 v[166:169], v66 offset:1840
	s_waitcnt vmcnt(0)
	s_waitcnt lgkmcnt(15)
	v_pk_mul_f32 v[224:225], v[90:91], v[102:103] op_sel:[0,0] op_sel_hi:[0,1]
	v_pk_mul_f32 v[226:227], v[90:91], v[104:105] op_sel:[0,0] op_sel_hi:[0,1]
	ds_read_b128 v[102:105], v66 offset:2048
	s_waitcnt lgkmcnt(15)
	v_pk_mul_f32 v[228:229], v[90:91], v[106:107] op_sel:[0,0] op_sel_hi:[0,1]
	v_pk_mul_f32 v[230:231], v[90:91], v[108:109] op_sel:[0,0] op_sel_hi:[0,1]
	ds_read_b128 v[106:109], v66 offset:2064
	s_waitcnt lgkmcnt(15)
	v_pk_mul_f32 v[232:233], v[90:91], v[110:111] op_sel:[0,0] op_sel_hi:[0,1]
	v_pk_mul_f32 v[234:235], v[90:91], v[112:113] op_sel:[0,0] op_sel_hi:[0,1]
	ds_read_b128 v[110:113], v66 offset:2080
	s_waitcnt lgkmcnt(15)
	v_pk_mul_f32 v[236:237], v[90:91], v[114:115] op_sel:[0,0] op_sel_hi:[0,1]
	v_pk_mul_f32 v[238:239], v[90:91], v[116:117] op_sel:[0,0] op_sel_hi:[0,1]
	ds_read_b128 v[114:117], v66 offset:2096
	s_waitcnt lgkmcnt(15)
	v_pk_fma_f32 v[224:225], v[90:91], v[118:119], v[224:225] op_sel:[1,0,0] op_sel_hi:[1,1,1]
	v_pk_fma_f32 v[226:227], v[90:91], v[120:121], v[226:227] op_sel:[1,0,0] op_sel_hi:[1,1,1]
	ds_read_b128 v[118:121], v66 offset:2304
	s_waitcnt lgkmcnt(15)
	v_pk_fma_f32 v[228:229], v[90:91], v[122:123], v[228:229] op_sel:[1,0,0] op_sel_hi:[1,1,1]
	v_pk_fma_f32 v[230:231], v[90:91], v[124:125], v[230:231] op_sel:[1,0,0] op_sel_hi:[1,1,1]
	ds_read_b128 v[122:125], v66 offset:2320
	s_waitcnt lgkmcnt(15)
	v_pk_fma_f32 v[232:233], v[90:91], v[126:127], v[232:233] op_sel:[1,0,0] op_sel_hi:[1,1,1]
	v_pk_fma_f32 v[234:235], v[90:91], v[128:129], v[234:235] op_sel:[1,0,0] op_sel_hi:[1,1,1]
	ds_read_b128 v[126:129], v66 offset:2336
	s_waitcnt lgkmcnt(15)
	v_pk_fma_f32 v[236:237], v[90:91], v[130:131], v[236:237] op_sel:[1,0,0] op_sel_hi:[1,1,1]
	v_pk_fma_f32 v[238:239], v[90:91], v[132:133], v[238:239] op_sel:[1,0,0] op_sel_hi:[1,1,1]
	ds_read_b128 v[130:133], v66 offset:2352
	s_waitcnt lgkmcnt(15)
	v_pk_fma_f32 v[224:225], v[92:93], v[134:135], v[224:225] op_sel:[0,0,0] op_sel_hi:[0,1,1]
	v_pk_fma_f32 v[226:227], v[92:93], v[136:137], v[226:227] op_sel:[0,0,0] op_sel_hi:[0,1,1]
	ds_read_b128 v[134:137], v66 offset:2560
	s_waitcnt lgkmcnt(15)
	v_pk_fma_f32 v[228:229], v[92:93], v[138:139], v[228:229] op_sel:[0,0,0] op_sel_hi:[0,1,1]
	v_pk_fma_f32 v[230:231], v[92:93], v[140:141], v[230:231] op_sel:[0,0,0] op_sel_hi:[0,1,1]
	ds_read_b128 v[138:141], v66 offset:2576
	s_waitcnt lgkmcnt(15)
	v_pk_fma_f32 v[232:233], v[92:93], v[142:143], v[232:233] op_sel:[0,0,0] op_sel_hi:[0,1,1]
	v_pk_fma_f32 v[234:235], v[92:93], v[144:145], v[234:235] op_sel:[0,0,0] op_sel_hi:[0,1,1]
	ds_read_b128 v[142:145], v66 offset:2592
	s_waitcnt lgkmcnt(15)
	v_pk_fma_f32 v[236:237], v[92:93], v[146:147], v[236:237] op_sel:[0,0,0] op_sel_hi:[0,1,1]
	v_pk_fma_f32 v[238:239], v[92:93], v[148:149], v[238:239] op_sel:[0,0,0] op_sel_hi:[0,1,1]
	ds_read_b128 v[146:149], v66 offset:2608
	s_waitcnt lgkmcnt(15)
	v_pk_fma_f32 v[224:225], v[92:93], v[150:151], v[224:225] op_sel:[1,0,0] op_sel_hi:[1,1,1]
	v_pk_fma_f32 v[226:227], v[92:93], v[152:153], v[226:227] op_sel:[1,0,0] op_sel_hi:[1,1,1]
	ds_read_b128 v[150:153], v66 offset:2816
	s_waitcnt lgkmcnt(15)
	v_pk_fma_f32 v[228:229], v[92:93], v[158:159], v[228:229] op_sel:[1,0,0] op_sel_hi:[1,1,1]
	v_pk_fma_f32 v[230:231], v[92:93], v[160:161], v[230:231] op_sel:[1,0,0] op_sel_hi:[1,1,1]
	ds_read_b128 v[158:161], v66 offset:2832
	s_waitcnt lgkmcnt(15)
	v_pk_fma_f32 v[232:233], v[92:93], v[162:163], v[232:233] op_sel:[1,0,0] op_sel_hi:[1,1,1]
	v_pk_fma_f32 v[234:235], v[92:93], v[164:165], v[234:235] op_sel:[1,0,0] op_sel_hi:[1,1,1]
	ds_read_b128 v[162:165], v66 offset:2848
	s_waitcnt lgkmcnt(15)
	v_pk_fma_f32 v[236:237], v[92:93], v[166:167], v[236:237] op_sel:[1,0,0] op_sel_hi:[1,1,1]
	v_pk_fma_f32 v[238:239], v[92:93], v[168:169], v[238:239] op_sel:[1,0,0] op_sel_hi:[1,1,1]
	ds_read_b128 v[166:169], v66 offset:2864
	s_waitcnt lgkmcnt(15)
	v_pk_fma_f32 v[224:225], v[86:87], v[102:103], v[224:225] op_sel:[0,0,0] op_sel_hi:[0,1,1]
	v_pk_fma_f32 v[226:227], v[86:87], v[104:105], v[226:227] op_sel:[0,0,0] op_sel_hi:[0,1,1]
	ds_read_b128 v[102:105], v66 offset:3072
	s_waitcnt lgkmcnt(15)
; #define LAS __attribute__((address_space(3)))
; __device__ __forceinline__ void phase_prep(const Params& p, LAS unsigned char* lds) {
;     ...
;             for (int c4 = 0; c4 < 16; ++c4) rw[c4] = *(const f32x4*)(row + 4 * c4);
; #pragma unroll
;             for (int c4 = 0; c4 < 16; ++c4)
; #pragma unroll
;                 for (int cc = 0; cc < 4; ++cc) { const float wv = rw[c4][cc]; const LAS f32x4* mp = (const LAS f32x4*)(Mf + (4 * c4 + cc) * 64 + eg * 16);
; #pragma unroll
;                     for (int j4 = 0; j4 < 4; ++j4) { const f32x4 mv = mp[j4]; a[4 * j4 + 0] += wv * mv[0]; a[4 * j4 + 1] += wv * mv[1]; a[4 * j4 + 2] += wv * mv[2]; a[4 * j4 + 3] += wv * mv[3]; } }
	v_pk_fma_f32 v[228:229], v[86:87], v[106:107], v[228:229] op_sel:[0,0,0] op_sel_hi:[0,1,1]
	v_pk_fma_f32 v[230:231], v[86:87], v[108:109], v[230:231] op_sel:[0,0,0] op_sel_hi:[0,1,1]
	ds_read_b128 v[106:109], v66 offset:3088
	s_waitcnt lgkmcnt(15)
	v_pk_fma_f32 v[232:233], v[86:87], v[110:111], v[232:233] op_sel:[0,0,0] op_sel_hi:[0,1,1]
	v_pk_fma_f32 v[234:235], v[86:87], v[112:113], v[234:235] op_sel:[0,0,0] op_sel_hi:[0,1,1]
	ds_read_b128 v[110:113], v66 offset:3104
	s_waitcnt lgkmcnt(15)
	v_pk_fma_f32 v[236:237], v[86:87], v[114:115], v[236:237] op_sel:[0,0,0] op_sel_hi:[0,1,1]
	v_pk_fma_f32 v[238:239], v[86:87], v[116:117], v[238:239] op_sel:[0,0,0] op_sel_hi:[0,1,1]
	ds_read_b128 v[114:117], v66 offset:3120
	s_waitcnt lgkmcnt(15)
	v_pk_fma_f32 v[224:225], v[86:87], v[118:119], v[224:225] op_sel:[1,0,0] op_sel_hi:[1,1,1]
	v_pk_fma_f32 v[226:227], v[86:87], v[120:121], v[226:227] op_sel:[1,0,0] op_sel_hi:[1,1,1]
	ds_read_b128 v[118:121], v66 offset:3328
	s_waitcnt lgkmcnt(15)
	v_pk_fma_f32 v[228:229], v[86:87], v[122:123], v[228:229] op_sel:[1,0,0] op_sel_hi:[1,1,1]
	v_pk_fma_f32 v[230:231], v[86:87], v[124:125], v[230:231] op_sel:[1,0,0] op_sel_hi:[1,1,1]
	ds_read_b128 v[122:125], v66 offset:3344
	s_waitcnt lgkmcnt(15)
	v_pk_fma_f32 v[232:233], v[86:87], v[126:127], v[232:233] op_sel:[1,0,0] op_sel_hi:[1,1,1]
	v_pk_fma_f32 v[234:235], v[86:87], v[128:129], v[234:235] op_sel:[1,0,0] op_sel_hi:[1,1,1]
	ds_read_b128 v[126:129], v66 offset:3360
	s_waitcnt lgkmcnt(15)
	v_pk_fma_f32 v[236:237], v[86:87], v[130:131], v[236:237] op_sel:[1,0,0] op_sel_hi:[1,1,1]
	v_pk_fma_f32 v[238:239], v[86:87], v[132:133], v[238:239] op_sel:[1,0,0] op_sel_hi:[1,1,1]
	ds_read_b128 v[130:133], v66 offset:3376
	s_waitcnt lgkmcnt(15)
	v_pk_fma_f32 v[224:225], v[88:89], v[134:135], v[224:225] op_sel:[0,0,0] op_sel_hi:[0,1,1]
	v_pk_fma_f32 v[226:227], v[88:89], v[136:137], v[226:227] op_sel:[0,0,0] op_sel_hi:[0,1,1]
	ds_read_b128 v[134:137], v66 offset:3584
	s_waitcnt lgkmcnt(15)
	v_pk_fma_f32 v[228:229], v[88:89], v[138:139], v[228:229] op_sel:[0,0,0] op_sel_hi:[0,1,1]
	v_pk_fma_f32 v[230:231], v[88:89], v[140:141], v[230:231] op_sel:[0,0,0] op_sel_hi:[0,1,1]
	ds_read_b128 v[138:141], v66 offset:3600
	s_waitcnt lgkmcnt(15)
	v_pk_fma_f32 v[232:233], v[88:89], v[142:143], v[232:233] op_sel:[0,0,0] op_sel_hi:[0,1,1]
	v_pk_fma_f32 v[234:235], v[88:89], v[144:145], v[234:235] op_sel:[0,0,0] op_sel_hi:[0,1,1]
	ds_read_b128 v[142:145], v66 offset:3616
	s_waitcnt lgkmcnt(15)
	v_pk_fma_f32 v[236:237], v[88:89], v[146:147], v[236:237] op_sel:[0,0,0] op_sel_hi:[0,1,1]
	v_pk_fma_f32 v[238:239], v[88:89], v[148:149], v[238:239] op_sel:[0,0,0] op_sel_hi:[0,1,1]
	ds_read_b128 v[146:149], v66 offset:3632
	s_waitcnt lgkmcnt(15)
	v_pk_fma_f32 v[224:225], v[88:89], v[150:151], v[224:225] op_sel:[1,0,0] op_sel_hi:[1,1,1]
	v_pk_fma_f32 v[226:227], v[88:89], v[152:153], v[226:227] op_sel:[1,0,0] op_sel_hi:[1,1,1]
	ds_read_b128 v[150:153], v66 offset:3840
	s_waitcnt lgkmcnt(15)
	v_pk_fma_f32 v[228:229], v[88:89], v[158:159], v[228:229] op_sel:[1,0,0] op_sel_hi:[1,1,1]
	v_pk_fma_f32 v[230:231], v[88:89], v[160:161], v[230:231] op_sel:[1,0,0] op_sel_hi:[1,1,1]
	ds_read_b128 v[158:161], v66 offset:3856
	s_waitcnt lgkmcnt(15)
	v_pk_fma_f32 v[232:233], v[88:89], v[162:163], v[232:233] op_sel:[1,0,0] op_sel_hi:[1,1,1]
	v_pk_fma_f32 v[234:235], v[88:89], v[164:165], v[234:235] op_sel:[1,0,0] op_sel_hi:[1,1,1]
	ds_read_b128 v[162:165], v66 offset:3872
	s_waitcnt lgkmcnt(15)
	v_pk_fma_f32 v[236:237], v[88:89], v[166:167], v[236:237] op_sel:[1,0,0] op_sel_hi:[1,1,1]
	v_pk_fma_f32 v[238:239], v[88:89], v[168:169], v[238:239] op_sel:[1,0,0] op_sel_hi:[1,1,1]
	ds_read_b128 v[166:169], v66 offset:3888
	s_waitcnt lgkmcnt(15)
	v_pk_fma_f32 v[224:225], v[52:53], v[102:103], v[224:225] op_sel:[0,0,0] op_sel_hi:[0,1,1]
	v_pk_fma_f32 v[226:227], v[52:53], v[104:105], v[226:227] op_sel:[0,0,0] op_sel_hi:[0,1,1]
	ds_read_b128 v[102:105], v66 offset:4096
	s_waitcnt lgkmcnt(15)
	v_pk_fma_f32 v[228:229], v[52:53], v[106:107], v[228:229] op_sel:[0,0,0] op_sel_hi:[0,1,1]
	v_pk_fma_f32 v[230:231], v[52:53], v[108:109], v[230:231] op_sel:[0,0,0] op_sel_hi:[0,1,1]
	ds_read_b128 v[106:109], v66 offset:4112
	s_waitcnt lgkmcnt(15)
	v_pk_fma_f32 v[232:233], v[52:53], v[110:111], v[232:233] op_sel:[0,0,0] op_sel_hi:[0,1,1]
	v_pk_fma_f32 v[234:235], v[52:53], v[112:113], v[234:235] op_sel:[0,0,0] op_sel_hi:[0,1,1]
	ds_read_b128 v[110:113], v66 offset:4128
	s_waitcnt lgkmcnt(15)
	v_pk_fma_f32 v[236:237], v[52:53], v[114:115], v[236:237] op_sel:[0,0,0] op_sel_hi:[0,1,1]
	v_pk_fma_f32 v[238:239], v[52:53], v[116:117], v[238:239] op_sel:[0,0,0] op_sel_hi:[0,1,1]
	ds_read_b128 v[114:117], v66 offset:4144
	s_waitcnt lgkmcnt(15)
	v_pk_fma_f32 v[224:225], v[52:53], v[118:119], v[224:225] op_sel:[1,0,0] op_sel_hi:[1,1,1]
	v_pk_fma_f32 v[226:227], v[52:53], v[120:121], v[226:227] op_sel:[1,0,0] op_sel_hi:[1,1,1]
	ds_read_b128 v[118:121], v66 offset:4352
	s_waitcnt lgkmcnt(15)
	v_pk_fma_f32 v[228:229], v[52:53], v[122:123], v[228:229] op_sel:[1,0,0] op_sel_hi:[1,1,1]
	v_pk_fma_f32 v[230:231], v[52:53], v[124:125], v[230:231] op_sel:[1,0,0] op_sel_hi:[1,1,1]
	ds_read_b128 v[122:125], v66 offset:4368
	s_waitcnt lgkmcnt(15)
	v_pk_fma_f32 v[232:233], v[52:53], v[126:127], v[232:233] op_sel:[1,0,0] op_sel_hi:[1,1,1]
	v_pk_fma_f32 v[234:235], v[52:53], v[128:129], v[234:235] op_sel:[1,0,0] op_sel_hi:[1,1,1]
	ds_read_b128 v[126:129], v66 offset:4384
	s_waitcnt lgkmcnt(15)
	v_pk_fma_f32 v[236:237], v[52:53], v[130:131], v[236:237] op_sel:[1,0,0] op_sel_hi:[1,1,1]
	v_pk_fma_f32 v[238:239], v[52:53], v[132:133], v[238:239] op_sel:[1,0,0] op_sel_hi:[1,1,1]
	ds_read_b128 v[130:133], v66 offset:4400
	s_waitcnt lgkmcnt(15)
; #define LAS __attribute__((address_space(3)))
; __device__ __forceinline__ void phase_prep(const Params& p, LAS unsigned char* lds) {
;     ...
;             for (int c4 = 0; c4 < 16; ++c4) rw[c4] = *(const f32x4*)(row + 4 * c4);
; #pragma unroll
;             for (int c4 = 0; c4 < 16; ++c4)
; #pragma unroll
;                 for (int cc = 0; cc < 4; ++cc) { const float wv = rw[c4][cc]; const LAS f32x4* mp = (const LAS f32x4*)(Mf + (4 * c4 + cc) * 64 + eg * 16);
; #pragma unroll
;                     for (int j4 = 0; j4 < 4; ++j4) { const f32x4 mv = mp[j4]; a[4 * j4 + 0] += wv * mv[0]; a[4 * j4 + 1] += wv * mv[1]; a[4 * j4 + 2] += wv * mv[2]; a[4 * j4 + 3] += wv * mv[3]; } }
	v_pk_fma_f32 v[224:225], v[54:55], v[134:135], v[224:225] op_sel:[0,0,0] op_sel_hi:[0,1,1]
	v_pk_fma_f32 v[226:227], v[54:55], v[136:137], v[226:227] op_sel:[0,0,0] op_sel_hi:[0,1,1]
	ds_read_b128 v[134:137], v66 offset:4608
	s_waitcnt lgkmcnt(15)
	v_pk_fma_f32 v[228:229], v[54:55], v[138:139], v[228:229] op_sel:[0,0,0] op_sel_hi:[0,1,1]
	v_pk_fma_f32 v[230:231], v[54:55], v[140:141], v[230:231] op_sel:[0,0,0] op_sel_hi:[0,1,1]
	ds_read_b128 v[138:141], v66 offset:4624
	s_waitcnt lgkmcnt(15)
	v_pk_fma_f32 v[232:233], v[54:55], v[142:143], v[232:233] op_sel:[0,0,0] op_sel_hi:[0,1,1]
	v_pk_fma_f32 v[234:235], v[54:55], v[144:145], v[234:235] op_sel:[0,0,0] op_sel_hi:[0,1,1]
	ds_read_b128 v[142:145], v66 offset:4640
	s_waitcnt lgkmcnt(15)
	v_pk_fma_f32 v[236:237], v[54:55], v[146:147], v[236:237] op_sel:[0,0,0] op_sel_hi:[0,1,1]
	v_pk_fma_f32 v[238:239], v[54:55], v[148:149], v[238:239] op_sel:[0,0,0] op_sel_hi:[0,1,1]
	ds_read_b128 v[146:149], v66 offset:4656
	s_waitcnt lgkmcnt(15)
	v_pk_fma_f32 v[224:225], v[54:55], v[150:151], v[224:225] op_sel:[1,0,0] op_sel_hi:[1,1,1]
	v_pk_fma_f32 v[226:227], v[54:55], v[152:153], v[226:227] op_sel:[1,0,0] op_sel_hi:[1,1,1]
	ds_read_b128 v[150:153], v66 offset:4864
	s_waitcnt lgkmcnt(15)
	v_pk_fma_f32 v[228:229], v[54:55], v[158:159], v[228:229] op_sel:[1,0,0] op_sel_hi:[1,1,1]
	v_pk_fma_f32 v[230:231], v[54:55], v[160:161], v[230:231] op_sel:[1,0,0] op_sel_hi:[1,1,1]
	ds_read_b128 v[158:161], v66 offset:4880
	s_waitcnt lgkmcnt(15)
	v_pk_fma_f32 v[232:233], v[54:55], v[162:163], v[232:233] op_sel:[1,0,0] op_sel_hi:[1,1,1]
	v_pk_fma_f32 v[234:235], v[54:55], v[164:165], v[234:235] op_sel:[1,0,0] op_sel_hi:[1,1,1]
	ds_read_b128 v[162:165], v66 offset:4896
	s_waitcnt lgkmcnt(15)
	v_pk_fma_f32 v[236:237], v[54:55], v[166:167], v[236:237] op_sel:[1,0,0] op_sel_hi:[1,1,1]
	v_pk_fma_f32 v[238:239], v[54:55], v[168:169], v[238:239] op_sel:[1,0,0] op_sel_hi:[1,1,1]
	ds_read_b128 v[166:169], v66 offset:4912
	s_waitcnt lgkmcnt(15)
	v_pk_fma_f32 v[224:225], v[48:49], v[102:103], v[224:225] op_sel:[0,0,0] op_sel_hi:[0,1,1]
	v_pk_fma_f32 v[226:227], v[48:49], v[104:105], v[226:227] op_sel:[0,0,0] op_sel_hi:[0,1,1]
	ds_read_b128 v[102:105], v66 offset:5120
	s_waitcnt lgkmcnt(15)
	v_pk_fma_f32 v[228:229], v[48:49], v[106:107], v[228:229] op_sel:[0,0,0] op_sel_hi:[0,1,1]
	v_pk_fma_f32 v[230:231], v[48:49], v[108:109], v[230:231] op_sel:[0,0,0] op_sel_hi:[0,1,1]
	ds_read_b128 v[106:109], v66 offset:5136
	s_waitcnt lgkmcnt(15)
	v_pk_fma_f32 v[232:233], v[48:49], v[110:111], v[232:233] op_sel:[0,0,0] op_sel_hi:[0,1,1]
	v_pk_fma_f32 v[234:235], v[48:49], v[112:113], v[234:235] op_sel:[0,0,0] op_sel_hi:[0,1,1]
	ds_read_b128 v[110:113], v66 offset:5152
	s_waitcnt lgkmcnt(15)
	v_pk_fma_f32 v[236:237], v[48:49], v[114:115], v[236:237] op_sel:[0,0,0] op_sel_hi:[0,1,1]
	v_pk_fma_f32 v[238:239], v[48:49], v[116:117], v[238:239] op_sel:[0,0,0] op_sel_hi:[0,1,1]
	ds_read_b128 v[114:117], v66 offset:5168
	s_waitcnt lgkmcnt(15)
	v_pk_fma_f32 v[224:225], v[48:49], v[118:119], v[224:225] op_sel:[1,0,0] op_sel_hi:[1,1,1]
	v_pk_fma_f32 v[226:227], v[48:49], v[120:121], v[226:227] op_sel:[1,0,0] op_sel_hi:[1,1,1]
	ds_read_b128 v[118:121], v66 offset:5376
	s_waitcnt lgkmcnt(15)
	v_pk_fma_f32 v[228:229], v[48:49], v[122:123], v[228:229] op_sel:[1,0,0] op_sel_hi:[1,1,1]
	v_pk_fma_f32 v[230:231], v[48:49], v[124:125], v[230:231] op_sel:[1,0,0] op_sel_hi:[1,1,1]
	ds_read_b128 v[122:125], v66 offset:5392
	s_waitcnt lgkmcnt(15)
	v_pk_fma_f32 v[232:233], v[48:49], v[126:127], v[232:233] op_sel:[1,0,0] op_sel_hi:[1,1,1]
	v_pk_fma_f32 v[234:235], v[48:49], v[128:129], v[234:235] op_sel:[1,0,0] op_sel_hi:[1,1,1]
	ds_read_b128 v[126:129], v66 offset:5408
	s_waitcnt lgkmcnt(15)
	v_pk_fma_f32 v[236:237], v[48:49], v[130:131], v[236:237] op_sel:[1,0,0] op_sel_hi:[1,1,1]
	v_pk_fma_f32 v[238:239], v[48:49], v[132:133], v[238:239] op_sel:[1,0,0] op_sel_hi:[1,1,1]
	ds_read_b128 v[130:133], v66 offset:5424
	s_waitcnt lgkmcnt(15)
	v_pk_fma_f32 v[224:225], v[50:51], v[134:135], v[224:225] op_sel:[0,0,0] op_sel_hi:[0,1,1]
	v_pk_fma_f32 v[226:227], v[50:51], v[136:137], v[226:227] op_sel:[0,0,0] op_sel_hi:[0,1,1]
	ds_read_b128 v[134:137], v66 offset:5632
	s_waitcnt lgkmcnt(15)
	v_pk_fma_f32 v[228:229], v[50:51], v[138:139], v[228:229] op_sel:[0,0,0] op_sel_hi:[0,1,1]
	v_pk_fma_f32 v[230:231], v[50:51], v[140:141], v[230:231] op_sel:[0,0,0] op_sel_hi:[0,1,1]
	ds_read_b128 v[138:141], v66 offset:5648
	s_waitcnt lgkmcnt(15)
	v_pk_fma_f32 v[232:233], v[50:51], v[142:143], v[232:233] op_sel:[0,0,0] op_sel_hi:[0,1,1]
	v_pk_fma_f32 v[234:235], v[50:51], v[144:145], v[234:235] op_sel:[0,0,0] op_sel_hi:[0,1,1]
	ds_read_b128 v[142:145], v66 offset:5664
	s_waitcnt lgkmcnt(15)
	v_pk_fma_f32 v[236:237], v[50:51], v[146:147], v[236:237] op_sel:[0,0,0] op_sel_hi:[0,1,1]
	v_pk_fma_f32 v[238:239], v[50:51], v[148:149], v[238:239] op_sel:[0,0,0] op_sel_hi:[0,1,1]
	ds_read_b128 v[146:149], v66 offset:5680
	s_waitcnt lgkmcnt(15)
	v_pk_fma_f32 v[224:225], v[50:51], v[150:151], v[224:225] op_sel:[1,0,0] op_sel_hi:[1,1,1]
	v_pk_fma_f32 v[226:227], v[50:51], v[152:153], v[226:227] op_sel:[1,0,0] op_sel_hi:[1,1,1]
	ds_read_b128 v[150:153], v66 offset:5888
	s_waitcnt lgkmcnt(15)
	v_pk_fma_f32 v[228:229], v[50:51], v[158:159], v[228:229] op_sel:[1,0,0] op_sel_hi:[1,1,1]
	v_pk_fma_f32 v[230:231], v[50:51], v[160:161], v[230:231] op_sel:[1,0,0] op_sel_hi:[1,1,1]
	ds_read_b128 v[158:161], v66 offset:5904
	s_waitcnt lgkmcnt(15)
	v_pk_fma_f32 v[232:233], v[50:51], v[162:163], v[232:233] op_sel:[1,0,0] op_sel_hi:[1,1,1]
	v_pk_fma_f32 v[234:235], v[50:51], v[164:165], v[234:235] op_sel:[1,0,0] op_sel_hi:[1,1,1]
	ds_read_b128 v[162:165], v66 offset:5920
	s_waitcnt lgkmcnt(15)
; #define LAS __attribute__((address_space(3)))
; __device__ __forceinline__ void phase_prep(const Params& p, LAS unsigned char* lds) {
;     ...
;             for (int c4 = 0; c4 < 16; ++c4) rw[c4] = *(const f32x4*)(row + 4 * c4);
; #pragma unroll
;             for (int c4 = 0; c4 < 16; ++c4)
; #pragma unroll
;                 for (int cc = 0; cc < 4; ++cc) { const float wv = rw[c4][cc]; const LAS f32x4* mp = (const LAS f32x4*)(Mf + (4 * c4 + cc) * 64 + eg * 16);
; #pragma unroll
;                     for (int j4 = 0; j4 < 4; ++j4) { const f32x4 mv = mp[j4]; a[4 * j4 + 0] += wv * mv[0]; a[4 * j4 + 1] += wv * mv[1]; a[4 * j4 + 2] += wv * mv[2]; a[4 * j4 + 3] += wv * mv[3]; } }
	v_pk_fma_f32 v[236:237], v[50:51], v[166:167], v[236:237] op_sel:[1,0,0] op_sel_hi:[1,1,1]
	v_pk_fma_f32 v[238:239], v[50:51], v[168:169], v[238:239] op_sel:[1,0,0] op_sel_hi:[1,1,1]
	ds_read_b128 v[166:169], v66 offset:5936
	s_waitcnt lgkmcnt(15)
	v_pk_fma_f32 v[224:225], v[44:45], v[102:103], v[224:225] op_sel:[0,0,0] op_sel_hi:[0,1,1]
	v_pk_fma_f32 v[226:227], v[44:45], v[104:105], v[226:227] op_sel:[0,0,0] op_sel_hi:[0,1,1]
	ds_read_b128 v[102:105], v66 offset:6144
	s_waitcnt lgkmcnt(15)
	v_pk_fma_f32 v[228:229], v[44:45], v[106:107], v[228:229] op_sel:[0,0,0] op_sel_hi:[0,1,1]
	v_pk_fma_f32 v[230:231], v[44:45], v[108:109], v[230:231] op_sel:[0,0,0] op_sel_hi:[0,1,1]
	ds_read_b128 v[106:109], v66 offset:6160
	s_waitcnt lgkmcnt(15)
	v_pk_fma_f32 v[232:233], v[44:45], v[110:111], v[232:233] op_sel:[0,0,0] op_sel_hi:[0,1,1]
	v_pk_fma_f32 v[234:235], v[44:45], v[112:113], v[234:235] op_sel:[0,0,0] op_sel_hi:[0,1,1]
	ds_read_b128 v[110:113], v66 offset:6176
	s_waitcnt lgkmcnt(15)
	v_pk_fma_f32 v[236:237], v[44:45], v[114:115], v[236:237] op_sel:[0,0,0] op_sel_hi:[0,1,1]
	v_pk_fma_f32 v[238:239], v[44:45], v[116:117], v[238:239] op_sel:[0,0,0] op_sel_hi:[0,1,1]
	ds_read_b128 v[114:117], v66 offset:6192
	s_waitcnt lgkmcnt(15)
	v_pk_fma_f32 v[224:225], v[44:45], v[118:119], v[224:225] op_sel:[1,0,0] op_sel_hi:[1,1,1]
	v_pk_fma_f32 v[226:227], v[44:45], v[120:121], v[226:227] op_sel:[1,0,0] op_sel_hi:[1,1,1]
	ds_read_b128 v[118:121], v66 offset:6400
	s_waitcnt lgkmcnt(15)
	v_pk_fma_f32 v[228:229], v[44:45], v[122:123], v[228:229] op_sel:[1,0,0] op_sel_hi:[1,1,1]
	v_pk_fma_f32 v[230:231], v[44:45], v[124:125], v[230:231] op_sel:[1,0,0] op_sel_hi:[1,1,1]
	ds_read_b128 v[122:125], v66 offset:6416
	s_waitcnt lgkmcnt(15)
	v_pk_fma_f32 v[232:233], v[44:45], v[126:127], v[232:233] op_sel:[1,0,0] op_sel_hi:[1,1,1]
	v_pk_fma_f32 v[234:235], v[44:45], v[128:129], v[234:235] op_sel:[1,0,0] op_sel_hi:[1,1,1]
	ds_read_b128 v[126:129], v66 offset:6432
	s_waitcnt lgkmcnt(15)
	v_pk_fma_f32 v[236:237], v[44:45], v[130:131], v[236:237] op_sel:[1,0,0] op_sel_hi:[1,1,1]
	v_pk_fma_f32 v[238:239], v[44:45], v[132:133], v[238:239] op_sel:[1,0,0] op_sel_hi:[1,1,1]
	ds_read_b128 v[130:133], v66 offset:6448
	s_waitcnt lgkmcnt(15)
	v_pk_fma_f32 v[224:225], v[46:47], v[134:135], v[224:225] op_sel:[0,0,0] op_sel_hi:[0,1,1]
	v_pk_fma_f32 v[226:227], v[46:47], v[136:137], v[226:227] op_sel:[0,0,0] op_sel_hi:[0,1,1]
	ds_read_b128 v[134:137], v66 offset:6656
	s_waitcnt lgkmcnt(15)
	v_pk_fma_f32 v[228:229], v[46:47], v[138:139], v[228:229] op_sel:[0,0,0] op_sel_hi:[0,1,1]
	v_pk_fma_f32 v[230:231], v[46:47], v[140:141], v[230:231] op_sel:[0,0,0] op_sel_hi:[0,1,1]
	ds_read_b128 v[138:141], v66 offset:6672
	s_waitcnt lgkmcnt(15)
	v_pk_fma_f32 v[232:233], v[46:47], v[142:143], v[232:233] op_sel:[0,0,0] op_sel_hi:[0,1,1]
	v_pk_fma_f32 v[234:235], v[46:47], v[144:145], v[234:235] op_sel:[0,0,0] op_sel_hi:[0,1,1]
	ds_read_b128 v[142:145], v66 offset:6688
	s_waitcnt lgkmcnt(15)
	v_pk_fma_f32 v[236:237], v[46:47], v[146:147], v[236:237] op_sel:[0,0,0] op_sel_hi:[0,1,1]
	v_pk_fma_f32 v[238:239], v[46:47], v[148:149], v[238:239] op_sel:[0,0,0] op_sel_hi:[0,1,1]
	ds_read_b128 v[146:149], v66 offset:6704
	s_waitcnt lgkmcnt(15)
	v_pk_fma_f32 v[224:225], v[46:47], v[150:151], v[224:225] op_sel:[1,0,0] op_sel_hi:[1,1,1]
	v_pk_fma_f32 v[226:227], v[46:47], v[152:153], v[226:227] op_sel:[1,0,0] op_sel_hi:[1,1,1]
	ds_read_b128 v[150:153], v66 offset:6912
	s_waitcnt lgkmcnt(15)
	v_pk_fma_f32 v[228:229], v[46:47], v[158:159], v[228:229] op_sel:[1,0,0] op_sel_hi:[1,1,1]
	v_pk_fma_f32 v[230:231], v[46:47], v[160:161], v[230:231] op_sel:[1,0,0] op_sel_hi:[1,1,1]
	ds_read_b128 v[158:161], v66 offset:6928
	s_waitcnt lgkmcnt(15)
	v_pk_fma_f32 v[232:233], v[46:47], v[162:163], v[232:233] op_sel:[1,0,0] op_sel_hi:[1,1,1]
	v_pk_fma_f32 v[234:235], v[46:47], v[164:165], v[234:235] op_sel:[1,0,0] op_sel_hi:[1,1,1]
	ds_read_b128 v[162:165], v66 offset:6944
	s_waitcnt lgkmcnt(15)
	v_pk_fma_f32 v[236:237], v[46:47], v[166:167], v[236:237] op_sel:[1,0,0] op_sel_hi:[1,1,1]
	v_pk_fma_f32 v[238:239], v[46:47], v[168:169], v[238:239] op_sel:[1,0,0] op_sel_hi:[1,1,1]
	ds_read_b128 v[166:169], v66 offset:6960
	s_waitcnt lgkmcnt(15)
	v_pk_fma_f32 v[224:225], v[40:41], v[102:103], v[224:225] op_sel:[0,0,0] op_sel_hi:[0,1,1]
	v_pk_fma_f32 v[226:227], v[40:41], v[104:105], v[226:227] op_sel:[0,0,0] op_sel_hi:[0,1,1]
	ds_read_b128 v[102:105], v66 offset:7168
	s_waitcnt lgkmcnt(15)
	v_pk_fma_f32 v[228:229], v[40:41], v[106:107], v[228:229] op_sel:[0,0,0] op_sel_hi:[0,1,1]
	v_pk_fma_f32 v[230:231], v[40:41], v[108:109], v[230:231] op_sel:[0,0,0] op_sel_hi:[0,1,1]
	ds_read_b128 v[106:109], v66 offset:7184
	s_waitcnt lgkmcnt(15)
	v_pk_fma_f32 v[232:233], v[40:41], v[110:111], v[232:233] op_sel:[0,0,0] op_sel_hi:[0,1,1]
	v_pk_fma_f32 v[234:235], v[40:41], v[112:113], v[234:235] op_sel:[0,0,0] op_sel_hi:[0,1,1]
	ds_read_b128 v[110:113], v66 offset:7200
	s_waitcnt lgkmcnt(15)
	v_pk_fma_f32 v[236:237], v[40:41], v[114:115], v[236:237] op_sel:[0,0,0] op_sel_hi:[0,1,1]
	v_pk_fma_f32 v[238:239], v[40:41], v[116:117], v[238:239] op_sel:[0,0,0] op_sel_hi:[0,1,1]
	ds_read_b128 v[114:117], v66 offset:7216
	s_waitcnt lgkmcnt(15)
	v_pk_fma_f32 v[224:225], v[40:41], v[118:119], v[224:225] op_sel:[1,0,0] op_sel_hi:[1,1,1]
	v_pk_fma_f32 v[226:227], v[40:41], v[120:121], v[226:227] op_sel:[1,0,0] op_sel_hi:[1,1,1]
	ds_read_b128 v[118:121], v66 offset:7424
	s_waitcnt lgkmcnt(15)
	v_pk_fma_f32 v[228:229], v[40:41], v[122:123], v[228:229] op_sel:[1,0,0] op_sel_hi:[1,1,1]
	v_pk_fma_f32 v[230:231], v[40:41], v[124:125], v[230:231] op_sel:[1,0,0] op_sel_hi:[1,1,1]
	ds_read_b128 v[122:125], v66 offset:7440
	s_waitcnt lgkmcnt(15)
; #define LAS __attribute__((address_space(3)))
; __device__ __forceinline__ void phase_prep(const Params& p, LAS unsigned char* lds) {
;     ...
;             for (int c4 = 0; c4 < 16; ++c4) rw[c4] = *(const f32x4*)(row + 4 * c4);
; #pragma unroll
;             for (int c4 = 0; c4 < 16; ++c4)
; #pragma unroll
;                 for (int cc = 0; cc < 4; ++cc) { const float wv = rw[c4][cc]; const LAS f32x4* mp = (const LAS f32x4*)(Mf + (4 * c4 + cc) * 64 + eg * 16);
; #pragma unroll
;                     for (int j4 = 0; j4 < 4; ++j4) { const f32x4 mv = mp[j4]; a[4 * j4 + 0] += wv * mv[0]; a[4 * j4 + 1] += wv * mv[1]; a[4 * j4 + 2] += wv * mv[2]; a[4 * j4 + 3] += wv * mv[3]; } }
	v_pk_fma_f32 v[232:233], v[40:41], v[126:127], v[232:233] op_sel:[1,0,0] op_sel_hi:[1,1,1]
	v_pk_fma_f32 v[234:235], v[40:41], v[128:129], v[234:235] op_sel:[1,0,0] op_sel_hi:[1,1,1]
	ds_read_b128 v[126:129], v66 offset:7456
	s_waitcnt lgkmcnt(15)
	v_pk_fma_f32 v[236:237], v[40:41], v[130:131], v[236:237] op_sel:[1,0,0] op_sel_hi:[1,1,1]
	v_pk_fma_f32 v[238:239], v[40:41], v[132:133], v[238:239] op_sel:[1,0,0] op_sel_hi:[1,1,1]
	ds_read_b128 v[130:133], v66 offset:7472
	s_waitcnt lgkmcnt(15)
	v_pk_fma_f32 v[224:225], v[42:43], v[134:135], v[224:225] op_sel:[0,0,0] op_sel_hi:[0,1,1]
	v_pk_fma_f32 v[226:227], v[42:43], v[136:137], v[226:227] op_sel:[0,0,0] op_sel_hi:[0,1,1]
	ds_read_b128 v[134:137], v66 offset:7680
	s_waitcnt lgkmcnt(15)
	v_pk_fma_f32 v[228:229], v[42:43], v[138:139], v[228:229] op_sel:[0,0,0] op_sel_hi:[0,1,1]
	v_pk_fma_f32 v[230:231], v[42:43], v[140:141], v[230:231] op_sel:[0,0,0] op_sel_hi:[0,1,1]
	ds_read_b128 v[138:141], v66 offset:7696
	s_waitcnt lgkmcnt(15)
	v_pk_fma_f32 v[232:233], v[42:43], v[142:143], v[232:233] op_sel:[0,0,0] op_sel_hi:[0,1,1]
	v_pk_fma_f32 v[234:235], v[42:43], v[144:145], v[234:235] op_sel:[0,0,0] op_sel_hi:[0,1,1]
	ds_read_b128 v[142:145], v66 offset:7712
	s_waitcnt lgkmcnt(15)
	v_pk_fma_f32 v[236:237], v[42:43], v[146:147], v[236:237] op_sel:[0,0,0] op_sel_hi:[0,1,1]
	v_pk_fma_f32 v[238:239], v[42:43], v[148:149], v[238:239] op_sel:[0,0,0] op_sel_hi:[0,1,1]
	ds_read_b128 v[146:149], v66 offset:7728
	s_waitcnt lgkmcnt(15)
	v_pk_fma_f32 v[224:225], v[42:43], v[150:151], v[224:225] op_sel:[1,0,0] op_sel_hi:[1,1,1]
	v_pk_fma_f32 v[226:227], v[42:43], v[152:153], v[226:227] op_sel:[1,0,0] op_sel_hi:[1,1,1]
	ds_read_b128 v[150:153], v66 offset:7936
	s_waitcnt lgkmcnt(15)
	v_pk_fma_f32 v[228:229], v[42:43], v[158:159], v[228:229] op_sel:[1,0,0] op_sel_hi:[1,1,1]
	v_pk_fma_f32 v[230:231], v[42:43], v[160:161], v[230:231] op_sel:[1,0,0] op_sel_hi:[1,1,1]
	ds_read_b128 v[158:161], v66 offset:7952
	s_waitcnt lgkmcnt(15)
	v_pk_fma_f32 v[232:233], v[42:43], v[162:163], v[232:233] op_sel:[1,0,0] op_sel_hi:[1,1,1]
	v_pk_fma_f32 v[234:235], v[42:43], v[164:165], v[234:235] op_sel:[1,0,0] op_sel_hi:[1,1,1]
	ds_read_b128 v[162:165], v66 offset:7968
	s_waitcnt lgkmcnt(15)
	v_pk_fma_f32 v[236:237], v[42:43], v[166:167], v[236:237] op_sel:[1,0,0] op_sel_hi:[1,1,1]
	v_pk_fma_f32 v[238:239], v[42:43], v[168:169], v[238:239] op_sel:[1,0,0] op_sel_hi:[1,1,1]
	ds_read_b128 v[166:169], v66 offset:7984
	s_waitcnt lgkmcnt(15)
	v_pk_fma_f32 v[224:225], v[36:37], v[102:103], v[224:225] op_sel:[0,0,0] op_sel_hi:[0,1,1]
	v_pk_fma_f32 v[226:227], v[36:37], v[104:105], v[226:227] op_sel:[0,0,0] op_sel_hi:[0,1,1]
	ds_read_b128 v[102:105], v66 offset:8192
	s_waitcnt lgkmcnt(15)
	v_pk_fma_f32 v[228:229], v[36:37], v[106:107], v[228:229] op_sel:[0,0,0] op_sel_hi:[0,1,1]
	v_pk_fma_f32 v[230:231], v[36:37], v[108:109], v[230:231] op_sel:[0,0,0] op_sel_hi:[0,1,1]
	ds_read_b128 v[106:109], v66 offset:8208
	s_waitcnt lgkmcnt(15)
	v_pk_fma_f32 v[232:233], v[36:37], v[110:111], v[232:233] op_sel:[0,0,0] op_sel_hi:[0,1,1]
	v_pk_fma_f32 v[234:235], v[36:37], v[112:113], v[234:235] op_sel:[0,0,0] op_sel_hi:[0,1,1]
	ds_read_b128 v[110:113], v66 offset:8224
	s_waitcnt lgkmcnt(15)
	v_pk_fma_f32 v[236:237], v[36:37], v[114:115], v[236:237] op_sel:[0,0,0] op_sel_hi:[0,1,1]
	v_pk_fma_f32 v[238:239], v[36:37], v[116:117], v[238:239] op_sel:[0,0,0] op_sel_hi:[0,1,1]
	ds_read_b128 v[114:117], v66 offset:8240
	s_waitcnt lgkmcnt(15)
	v_pk_fma_f32 v[224:225], v[36:37], v[118:119], v[224:225] op_sel:[1,0,0] op_sel_hi:[1,1,1]
	v_pk_fma_f32 v[226:227], v[36:37], v[120:121], v[226:227] op_sel:[1,0,0] op_sel_hi:[1,1,1]
	ds_read_b128 v[118:121], v66 offset:8448
	s_waitcnt lgkmcnt(15)
	v_pk_fma_f32 v[228:229], v[36:37], v[122:123], v[228:229] op_sel:[1,0,0] op_sel_hi:[1,1,1]
	v_pk_fma_f32 v[230:231], v[36:37], v[124:125], v[230:231] op_sel:[1,0,0] op_sel_hi:[1,1,1]
	ds_read_b128 v[122:125], v66 offset:8464
	s_waitcnt lgkmcnt(15)
	v_pk_fma_f32 v[232:233], v[36:37], v[126:127], v[232:233] op_sel:[1,0,0] op_sel_hi:[1,1,1]
	v_pk_fma_f32 v[234:235], v[36:37], v[128:129], v[234:235] op_sel:[1,0,0] op_sel_hi:[1,1,1]
	ds_read_b128 v[126:129], v66 offset:8480
	s_waitcnt lgkmcnt(15)
	v_pk_fma_f32 v[236:237], v[36:37], v[130:131], v[236:237] op_sel:[1,0,0] op_sel_hi:[1,1,1]
	v_pk_fma_f32 v[238:239], v[36:37], v[132:133], v[238:239] op_sel:[1,0,0] op_sel_hi:[1,1,1]
	ds_read_b128 v[130:133], v66 offset:8496
	s_waitcnt lgkmcnt(15)
	v_pk_fma_f32 v[224:225], v[38:39], v[134:135], v[224:225] op_sel:[0,0,0] op_sel_hi:[0,1,1]
	v_pk_fma_f32 v[226:227], v[38:39], v[136:137], v[226:227] op_sel:[0,0,0] op_sel_hi:[0,1,1]
	ds_read_b128 v[134:137], v66 offset:8704
	s_waitcnt lgkmcnt(15)
	v_pk_fma_f32 v[228:229], v[38:39], v[138:139], v[228:229] op_sel:[0,0,0] op_sel_hi:[0,1,1]
	v_pk_fma_f32 v[230:231], v[38:39], v[140:141], v[230:231] op_sel:[0,0,0] op_sel_hi:[0,1,1]
	ds_read_b128 v[138:141], v66 offset:8720
	s_waitcnt lgkmcnt(15)
	v_pk_fma_f32 v[232:233], v[38:39], v[142:143], v[232:233] op_sel:[0,0,0] op_sel_hi:[0,1,1]
	v_pk_fma_f32 v[234:235], v[38:39], v[144:145], v[234:235] op_sel:[0,0,0] op_sel_hi:[0,1,1]
	ds_read_b128 v[142:145], v66 offset:8736
	s_waitcnt lgkmcnt(15)
	v_pk_fma_f32 v[236:237], v[38:39], v[146:147], v[236:237] op_sel:[0,0,0] op_sel_hi:[0,1,1]
	v_pk_fma_f32 v[238:239], v[38:39], v[148:149], v[238:239] op_sel:[0,0,0] op_sel_hi:[0,1,1]
	ds_read_b128 v[146:149], v66 offset:8752
	s_waitcnt lgkmcnt(15)
	v_pk_fma_f32 v[224:225], v[38:39], v[150:151], v[224:225] op_sel:[1,0,0] op_sel_hi:[1,1,1]
	v_pk_fma_f32 v[226:227], v[38:39], v[152:153], v[226:227] op_sel:[1,0,0] op_sel_hi:[1,1,1]
	ds_read_b128 v[150:153], v66 offset:8960
	s_waitcnt lgkmcnt(15)
; #define LAS __attribute__((address_space(3)))
; __device__ __forceinline__ void phase_prep(const Params& p, LAS unsigned char* lds) {
;     ...
;             for (int c4 = 0; c4 < 16; ++c4) rw[c4] = *(const f32x4*)(row + 4 * c4);
; #pragma unroll
;             for (int c4 = 0; c4 < 16; ++c4)
; #pragma unroll
;                 for (int cc = 0; cc < 4; ++cc) { const float wv = rw[c4][cc]; const LAS f32x4* mp = (const LAS f32x4*)(Mf + (4 * c4 + cc) * 64 + eg * 16);
; #pragma unroll
;                     for (int j4 = 0; j4 < 4; ++j4) { const f32x4 mv = mp[j4]; a[4 * j4 + 0] += wv * mv[0]; a[4 * j4 + 1] += wv * mv[1]; a[4 * j4 + 2] += wv * mv[2]; a[4 * j4 + 3] += wv * mv[3]; } }
	v_pk_fma_f32 v[228:229], v[38:39], v[158:159], v[228:229] op_sel:[1,0,0] op_sel_hi:[1,1,1]
	v_pk_fma_f32 v[230:231], v[38:39], v[160:161], v[230:231] op_sel:[1,0,0] op_sel_hi:[1,1,1]
	ds_read_b128 v[158:161], v66 offset:8976
	s_waitcnt lgkmcnt(15)
	v_pk_fma_f32 v[232:233], v[38:39], v[162:163], v[232:233] op_sel:[1,0,0] op_sel_hi:[1,1,1]
	v_pk_fma_f32 v[234:235], v[38:39], v[164:165], v[234:235] op_sel:[1,0,0] op_sel_hi:[1,1,1]
	ds_read_b128 v[162:165], v66 offset:8992
	s_waitcnt lgkmcnt(15)
	v_pk_fma_f32 v[236:237], v[38:39], v[166:167], v[236:237] op_sel:[1,0,0] op_sel_hi:[1,1,1]
	v_pk_fma_f32 v[238:239], v[38:39], v[168:169], v[238:239] op_sel:[1,0,0] op_sel_hi:[1,1,1]
	ds_read_b128 v[166:169], v66 offset:9008
	s_waitcnt lgkmcnt(15)
	v_pk_fma_f32 v[224:225], v[32:33], v[102:103], v[224:225] op_sel:[0,0,0] op_sel_hi:[0,1,1]
	v_pk_fma_f32 v[226:227], v[32:33], v[104:105], v[226:227] op_sel:[0,0,0] op_sel_hi:[0,1,1]
	ds_read_b128 v[102:105], v66 offset:9216
	s_waitcnt lgkmcnt(15)
	v_pk_fma_f32 v[228:229], v[32:33], v[106:107], v[228:229] op_sel:[0,0,0] op_sel_hi:[0,1,1]
	v_pk_fma_f32 v[230:231], v[32:33], v[108:109], v[230:231] op_sel:[0,0,0] op_sel_hi:[0,1,1]
	ds_read_b128 v[106:109], v66 offset:9232
	s_waitcnt lgkmcnt(15)
	v_pk_fma_f32 v[232:233], v[32:33], v[110:111], v[232:233] op_sel:[0,0,0] op_sel_hi:[0,1,1]
	v_pk_fma_f32 v[234:235], v[32:33], v[112:113], v[234:235] op_sel:[0,0,0] op_sel_hi:[0,1,1]
	ds_read_b128 v[110:113], v66 offset:9248
	s_waitcnt lgkmcnt(15)
	v_pk_fma_f32 v[236:237], v[32:33], v[114:115], v[236:237] op_sel:[0,0,0] op_sel_hi:[0,1,1]
	v_pk_fma_f32 v[238:239], v[32:33], v[116:117], v[238:239] op_sel:[0,0,0] op_sel_hi:[0,1,1]
	ds_read_b128 v[114:117], v66 offset:9264
	s_waitcnt lgkmcnt(15)
	v_pk_fma_f32 v[224:225], v[32:33], v[118:119], v[224:225] op_sel:[1,0,0] op_sel_hi:[1,1,1]
	v_pk_fma_f32 v[226:227], v[32:33], v[120:121], v[226:227] op_sel:[1,0,0] op_sel_hi:[1,1,1]
	ds_read_b128 v[118:121], v66 offset:9472
	s_waitcnt lgkmcnt(15)
	v_pk_fma_f32 v[228:229], v[32:33], v[122:123], v[228:229] op_sel:[1,0,0] op_sel_hi:[1,1,1]
	v_pk_fma_f32 v[230:231], v[32:33], v[124:125], v[230:231] op_sel:[1,0,0] op_sel_hi:[1,1,1]
	ds_read_b128 v[122:125], v66 offset:9488
	s_waitcnt lgkmcnt(15)
	v_pk_fma_f32 v[232:233], v[32:33], v[126:127], v[232:233] op_sel:[1,0,0] op_sel_hi:[1,1,1]
	v_pk_fma_f32 v[234:235], v[32:33], v[128:129], v[234:235] op_sel:[1,0,0] op_sel_hi:[1,1,1]
	ds_read_b128 v[126:129], v66 offset:9504
	s_waitcnt lgkmcnt(15)
	v_pk_fma_f32 v[236:237], v[32:33], v[130:131], v[236:237] op_sel:[1,0,0] op_sel_hi:[1,1,1]
	v_pk_fma_f32 v[238:239], v[32:33], v[132:133], v[238:239] op_sel:[1,0,0] op_sel_hi:[1,1,1]
	ds_read_b128 v[130:133], v66 offset:9520
	s_waitcnt lgkmcnt(15)
	v_pk_fma_f32 v[224:225], v[34:35], v[134:135], v[224:225] op_sel:[0,0,0] op_sel_hi:[0,1,1]
	v_pk_fma_f32 v[226:227], v[34:35], v[136:137], v[226:227] op_sel:[0,0,0] op_sel_hi:[0,1,1]
	ds_read_b128 v[134:137], v66 offset:9728
	s_waitcnt lgkmcnt(15)
	v_pk_fma_f32 v[228:229], v[34:35], v[138:139], v[228:229] op_sel:[0,0,0] op_sel_hi:[0,1,1]
	v_pk_fma_f32 v[230:231], v[34:35], v[140:141], v[230:231] op_sel:[0,0,0] op_sel_hi:[0,1,1]
	ds_read_b128 v[138:141], v66 offset:9744
	s_waitcnt lgkmcnt(15)
	v_pk_fma_f32 v[232:233], v[34:35], v[142:143], v[232:233] op_sel:[0,0,0] op_sel_hi:[0,1,1]
	v_pk_fma_f32 v[234:235], v[34:35], v[144:145], v[234:235] op_sel:[0,0,0] op_sel_hi:[0,1,1]
	ds_read_b128 v[142:145], v66 offset:9760
	s_waitcnt lgkmcnt(15)
	v_pk_fma_f32 v[236:237], v[34:35], v[146:147], v[236:237] op_sel:[0,0,0] op_sel_hi:[0,1,1]
	v_pk_fma_f32 v[238:239], v[34:35], v[148:149], v[238:239] op_sel:[0,0,0] op_sel_hi:[0,1,1]
	ds_read_b128 v[146:149], v66 offset:9776
	s_waitcnt lgkmcnt(15)
	v_pk_fma_f32 v[224:225], v[34:35], v[150:151], v[224:225] op_sel:[1,0,0] op_sel_hi:[1,1,1]
	v_pk_fma_f32 v[226:227], v[34:35], v[152:153], v[226:227] op_sel:[1,0,0] op_sel_hi:[1,1,1]
	ds_read_b128 v[150:153], v66 offset:9984
	s_waitcnt lgkmcnt(15)
	v_pk_fma_f32 v[228:229], v[34:35], v[158:159], v[228:229] op_sel:[1,0,0] op_sel_hi:[1,1,1]
	v_pk_fma_f32 v[230:231], v[34:35], v[160:161], v[230:231] op_sel:[1,0,0] op_sel_hi:[1,1,1]
	ds_read_b128 v[158:161], v66 offset:10000
	s_waitcnt lgkmcnt(15)
	v_pk_fma_f32 v[232:233], v[34:35], v[162:163], v[232:233] op_sel:[1,0,0] op_sel_hi:[1,1,1]
	v_pk_fma_f32 v[234:235], v[34:35], v[164:165], v[234:235] op_sel:[1,0,0] op_sel_hi:[1,1,1]
	ds_read_b128 v[162:165], v66 offset:10016
	s_waitcnt lgkmcnt(15)
	v_pk_fma_f32 v[236:237], v[34:35], v[166:167], v[236:237] op_sel:[1,0,0] op_sel_hi:[1,1,1]
	v_pk_fma_f32 v[238:239], v[34:35], v[168:169], v[238:239] op_sel:[1,0,0] op_sel_hi:[1,1,1]
	ds_read_b128 v[166:169], v66 offset:10032
	s_waitcnt lgkmcnt(15)
	v_pk_fma_f32 v[224:225], v[28:29], v[102:103], v[224:225] op_sel:[0,0,0] op_sel_hi:[0,1,1]
	v_pk_fma_f32 v[226:227], v[28:29], v[104:105], v[226:227] op_sel:[0,0,0] op_sel_hi:[0,1,1]
	ds_read_b128 v[102:105], v66 offset:10240
	s_waitcnt lgkmcnt(15)
	v_pk_fma_f32 v[228:229], v[28:29], v[106:107], v[228:229] op_sel:[0,0,0] op_sel_hi:[0,1,1]
	v_pk_fma_f32 v[230:231], v[28:29], v[108:109], v[230:231] op_sel:[0,0,0] op_sel_hi:[0,1,1]
	ds_read_b128 v[106:109], v66 offset:10256
	s_waitcnt lgkmcnt(15)
	v_pk_fma_f32 v[232:233], v[28:29], v[110:111], v[232:233] op_sel:[0,0,0] op_sel_hi:[0,1,1]
	v_pk_fma_f32 v[234:235], v[28:29], v[112:113], v[234:235] op_sel:[0,0,0] op_sel_hi:[0,1,1]
	ds_read_b128 v[110:113], v66 offset:10272
	s_waitcnt lgkmcnt(15)
	v_pk_fma_f32 v[236:237], v[28:29], v[114:115], v[236:237] op_sel:[0,0,0] op_sel_hi:[0,1,1]
	v_pk_fma_f32 v[238:239], v[28:29], v[116:117], v[238:239] op_sel:[0,0,0] op_sel_hi:[0,1,1]
	ds_read_b128 v[114:117], v66 offset:10288
	s_waitcnt lgkmcnt(15)
; #define LAS __attribute__((address_space(3)))
; __device__ __forceinline__ void phase_prep(const Params& p, LAS unsigned char* lds) {
;     ...
;             for (int c4 = 0; c4 < 16; ++c4) rw[c4] = *(const f32x4*)(row + 4 * c4);
; #pragma unroll
;             for (int c4 = 0; c4 < 16; ++c4)
; #pragma unroll
;                 for (int cc = 0; cc < 4; ++cc) { const float wv = rw[c4][cc]; const LAS f32x4* mp = (const LAS f32x4*)(Mf + (4 * c4 + cc) * 64 + eg * 16);
; #pragma unroll
;                     for (int j4 = 0; j4 < 4; ++j4) { const f32x4 mv = mp[j4]; a[4 * j4 + 0] += wv * mv[0]; a[4 * j4 + 1] += wv * mv[1]; a[4 * j4 + 2] += wv * mv[2]; a[4 * j4 + 3] += wv * mv[3]; } }
	v_pk_fma_f32 v[224:225], v[28:29], v[118:119], v[224:225] op_sel:[1,0,0] op_sel_hi:[1,1,1]
	v_pk_fma_f32 v[226:227], v[28:29], v[120:121], v[226:227] op_sel:[1,0,0] op_sel_hi:[1,1,1]
	ds_read_b128 v[118:121], v66 offset:10496
	s_waitcnt lgkmcnt(15)
	v_pk_fma_f32 v[228:229], v[28:29], v[122:123], v[228:229] op_sel:[1,0,0] op_sel_hi:[1,1,1]
	v_pk_fma_f32 v[230:231], v[28:29], v[124:125], v[230:231] op_sel:[1,0,0] op_sel_hi:[1,1,1]
	ds_read_b128 v[122:125], v66 offset:10512
	s_waitcnt lgkmcnt(15)
	v_pk_fma_f32 v[232:233], v[28:29], v[126:127], v[232:233] op_sel:[1,0,0] op_sel_hi:[1,1,1]
	v_pk_fma_f32 v[234:235], v[28:29], v[128:129], v[234:235] op_sel:[1,0,0] op_sel_hi:[1,1,1]
	ds_read_b128 v[126:129], v66 offset:10528
	s_waitcnt lgkmcnt(15)
	v_pk_fma_f32 v[236:237], v[28:29], v[130:131], v[236:237] op_sel:[1,0,0] op_sel_hi:[1,1,1]
	v_pk_fma_f32 v[238:239], v[28:29], v[132:133], v[238:239] op_sel:[1,0,0] op_sel_hi:[1,1,1]
	ds_read_b128 v[130:133], v66 offset:10544
	s_waitcnt lgkmcnt(15)
	v_pk_fma_f32 v[224:225], v[30:31], v[134:135], v[224:225] op_sel:[0,0,0] op_sel_hi:[0,1,1]
	v_pk_fma_f32 v[226:227], v[30:31], v[136:137], v[226:227] op_sel:[0,0,0] op_sel_hi:[0,1,1]
	ds_read_b128 v[134:137], v66 offset:10752
	s_waitcnt lgkmcnt(15)
	v_pk_fma_f32 v[228:229], v[30:31], v[138:139], v[228:229] op_sel:[0,0,0] op_sel_hi:[0,1,1]
	v_pk_fma_f32 v[230:231], v[30:31], v[140:141], v[230:231] op_sel:[0,0,0] op_sel_hi:[0,1,1]
	ds_read_b128 v[138:141], v66 offset:10768
	s_waitcnt lgkmcnt(15)
	v_pk_fma_f32 v[232:233], v[30:31], v[142:143], v[232:233] op_sel:[0,0,0] op_sel_hi:[0,1,1]
	v_pk_fma_f32 v[234:235], v[30:31], v[144:145], v[234:235] op_sel:[0,0,0] op_sel_hi:[0,1,1]
	ds_read_b128 v[142:145], v66 offset:10784
	s_waitcnt lgkmcnt(15)
	v_pk_fma_f32 v[236:237], v[30:31], v[146:147], v[236:237] op_sel:[0,0,0] op_sel_hi:[0,1,1]
	v_pk_fma_f32 v[238:239], v[30:31], v[148:149], v[238:239] op_sel:[0,0,0] op_sel_hi:[0,1,1]
	ds_read_b128 v[146:149], v66 offset:10800
	s_waitcnt lgkmcnt(15)
	v_pk_fma_f32 v[224:225], v[30:31], v[150:151], v[224:225] op_sel:[1,0,0] op_sel_hi:[1,1,1]
	v_pk_fma_f32 v[226:227], v[30:31], v[152:153], v[226:227] op_sel:[1,0,0] op_sel_hi:[1,1,1]
	ds_read_b128 v[150:153], v66 offset:11008
	s_waitcnt lgkmcnt(15)
	v_pk_fma_f32 v[228:229], v[30:31], v[158:159], v[228:229] op_sel:[1,0,0] op_sel_hi:[1,1,1]
	v_pk_fma_f32 v[230:231], v[30:31], v[160:161], v[230:231] op_sel:[1,0,0] op_sel_hi:[1,1,1]
	ds_read_b128 v[158:161], v66 offset:11024
	s_waitcnt lgkmcnt(15)
	v_pk_fma_f32 v[232:233], v[30:31], v[162:163], v[232:233] op_sel:[1,0,0] op_sel_hi:[1,1,1]
	v_pk_fma_f32 v[234:235], v[30:31], v[164:165], v[234:235] op_sel:[1,0,0] op_sel_hi:[1,1,1]
	ds_read_b128 v[162:165], v66 offset:11040
	s_waitcnt lgkmcnt(15)
	v_pk_fma_f32 v[236:237], v[30:31], v[166:167], v[236:237] op_sel:[1,0,0] op_sel_hi:[1,1,1]
	v_pk_fma_f32 v[238:239], v[30:31], v[168:169], v[238:239] op_sel:[1,0,0] op_sel_hi:[1,1,1]
	ds_read_b128 v[166:169], v66 offset:11056
	s_waitcnt lgkmcnt(15)
	v_pk_fma_f32 v[224:225], v[24:25], v[102:103], v[224:225] op_sel:[0,0,0] op_sel_hi:[0,1,1]
	v_pk_fma_f32 v[226:227], v[24:25], v[104:105], v[226:227] op_sel:[0,0,0] op_sel_hi:[0,1,1]
	ds_read_b128 v[102:105], v66 offset:11264
	s_waitcnt lgkmcnt(15)
	v_pk_fma_f32 v[228:229], v[24:25], v[106:107], v[228:229] op_sel:[0,0,0] op_sel_hi:[0,1,1]
	v_pk_fma_f32 v[230:231], v[24:25], v[108:109], v[230:231] op_sel:[0,0,0] op_sel_hi:[0,1,1]
	ds_read_b128 v[106:109], v66 offset:11280
	s_waitcnt lgkmcnt(15)
	v_pk_fma_f32 v[232:233], v[24:25], v[110:111], v[232:233] op_sel:[0,0,0] op_sel_hi:[0,1,1]
	v_pk_fma_f32 v[234:235], v[24:25], v[112:113], v[234:235] op_sel:[0,0,0] op_sel_hi:[0,1,1]
	ds_read_b128 v[110:113], v66 offset:11296
	s_waitcnt lgkmcnt(15)
	v_pk_fma_f32 v[236:237], v[24:25], v[114:115], v[236:237] op_sel:[0,0,0] op_sel_hi:[0,1,1]
	v_pk_fma_f32 v[238:239], v[24:25], v[116:117], v[238:239] op_sel:[0,0,0] op_sel_hi:[0,1,1]
	ds_read_b128 v[114:117], v66 offset:11312
	s_waitcnt lgkmcnt(15)
	v_pk_fma_f32 v[224:225], v[24:25], v[118:119], v[224:225] op_sel:[1,0,0] op_sel_hi:[1,1,1]
	v_pk_fma_f32 v[226:227], v[24:25], v[120:121], v[226:227] op_sel:[1,0,0] op_sel_hi:[1,1,1]
	ds_read_b128 v[118:121], v66 offset:11520
	s_waitcnt lgkmcnt(15)
	v_pk_fma_f32 v[228:229], v[24:25], v[122:123], v[228:229] op_sel:[1,0,0] op_sel_hi:[1,1,1]
	v_pk_fma_f32 v[230:231], v[24:25], v[124:125], v[230:231] op_sel:[1,0,0] op_sel_hi:[1,1,1]
	ds_read_b128 v[122:125], v66 offset:11536
	s_waitcnt lgkmcnt(15)
	v_pk_fma_f32 v[232:233], v[24:25], v[126:127], v[232:233] op_sel:[1,0,0] op_sel_hi:[1,1,1]
	v_pk_fma_f32 v[234:235], v[24:25], v[128:129], v[234:235] op_sel:[1,0,0] op_sel_hi:[1,1,1]
	ds_read_b128 v[126:129], v66 offset:11552
	s_waitcnt lgkmcnt(15)
	v_pk_fma_f32 v[236:237], v[24:25], v[130:131], v[236:237] op_sel:[1,0,0] op_sel_hi:[1,1,1]
	v_pk_fma_f32 v[238:239], v[24:25], v[132:133], v[238:239] op_sel:[1,0,0] op_sel_hi:[1,1,1]
	ds_read_b128 v[130:133], v66 offset:11568
	s_waitcnt lgkmcnt(15)
	v_pk_fma_f32 v[224:225], v[26:27], v[134:135], v[224:225] op_sel:[0,0,0] op_sel_hi:[0,1,1]
	v_pk_fma_f32 v[226:227], v[26:27], v[136:137], v[226:227] op_sel:[0,0,0] op_sel_hi:[0,1,1]
	ds_read_b128 v[134:137], v66 offset:11776
	s_waitcnt lgkmcnt(15)
	v_pk_fma_f32 v[228:229], v[26:27], v[138:139], v[228:229] op_sel:[0,0,0] op_sel_hi:[0,1,1]
	v_pk_fma_f32 v[230:231], v[26:27], v[140:141], v[230:231] op_sel:[0,0,0] op_sel_hi:[0,1,1]
	ds_read_b128 v[138:141], v66 offset:11792
	s_waitcnt lgkmcnt(15)
	v_pk_fma_f32 v[232:233], v[26:27], v[142:143], v[232:233] op_sel:[0,0,0] op_sel_hi:[0,1,1]
	v_pk_fma_f32 v[234:235], v[26:27], v[144:145], v[234:235] op_sel:[0,0,0] op_sel_hi:[0,1,1]
	ds_read_b128 v[142:145], v66 offset:11808
	s_waitcnt lgkmcnt(15)
; #define LAS __attribute__((address_space(3)))
; __device__ __forceinline__ void phase_prep(const Params& p, LAS unsigned char* lds) {
;     ...
;             for (int c4 = 0; c4 < 16; ++c4) rw[c4] = *(const f32x4*)(row + 4 * c4);
; #pragma unroll
;             for (int c4 = 0; c4 < 16; ++c4)
; #pragma unroll
;                 for (int cc = 0; cc < 4; ++cc) { const float wv = rw[c4][cc]; const LAS f32x4* mp = (const LAS f32x4*)(Mf + (4 * c4 + cc) * 64 + eg * 16);
; #pragma unroll
;                     for (int j4 = 0; j4 < 4; ++j4) { const f32x4 mv = mp[j4]; a[4 * j4 + 0] += wv * mv[0]; a[4 * j4 + 1] += wv * mv[1]; a[4 * j4 + 2] += wv * mv[2]; a[4 * j4 + 3] += wv * mv[3]; } }
	v_pk_fma_f32 v[236:237], v[26:27], v[146:147], v[236:237] op_sel:[0,0,0] op_sel_hi:[0,1,1]
	v_pk_fma_f32 v[238:239], v[26:27], v[148:149], v[238:239] op_sel:[0,0,0] op_sel_hi:[0,1,1]
	ds_read_b128 v[146:149], v66 offset:11824
	s_waitcnt lgkmcnt(15)
	v_pk_fma_f32 v[224:225], v[26:27], v[150:151], v[224:225] op_sel:[1,0,0] op_sel_hi:[1,1,1]
	v_pk_fma_f32 v[226:227], v[26:27], v[152:153], v[226:227] op_sel:[1,0,0] op_sel_hi:[1,1,1]
	ds_read_b128 v[150:153], v66 offset:12032
	s_waitcnt lgkmcnt(15)
	v_pk_fma_f32 v[228:229], v[26:27], v[158:159], v[228:229] op_sel:[1,0,0] op_sel_hi:[1,1,1]
	v_pk_fma_f32 v[230:231], v[26:27], v[160:161], v[230:231] op_sel:[1,0,0] op_sel_hi:[1,1,1]
	ds_read_b128 v[158:161], v66 offset:12048
	s_waitcnt lgkmcnt(15)
	v_pk_fma_f32 v[232:233], v[26:27], v[162:163], v[232:233] op_sel:[1,0,0] op_sel_hi:[1,1,1]
	v_pk_fma_f32 v[234:235], v[26:27], v[164:165], v[234:235] op_sel:[1,0,0] op_sel_hi:[1,1,1]
	ds_read_b128 v[162:165], v66 offset:12064
	s_waitcnt lgkmcnt(15)
	v_pk_fma_f32 v[236:237], v[26:27], v[166:167], v[236:237] op_sel:[1,0,0] op_sel_hi:[1,1,1]
	v_pk_fma_f32 v[238:239], v[26:27], v[168:169], v[238:239] op_sel:[1,0,0] op_sel_hi:[1,1,1]
	ds_read_b128 v[166:169], v66 offset:12080
	s_waitcnt lgkmcnt(15)
	v_pk_fma_f32 v[224:225], v[20:21], v[102:103], v[224:225] op_sel:[0,0,0] op_sel_hi:[0,1,1]
	v_pk_fma_f32 v[226:227], v[20:21], v[104:105], v[226:227] op_sel:[0,0,0] op_sel_hi:[0,1,1]
	ds_read_b128 v[102:105], v66 offset:12288
	s_waitcnt lgkmcnt(15)
	v_pk_fma_f32 v[228:229], v[20:21], v[106:107], v[228:229] op_sel:[0,0,0] op_sel_hi:[0,1,1]
	v_pk_fma_f32 v[230:231], v[20:21], v[108:109], v[230:231] op_sel:[0,0,0] op_sel_hi:[0,1,1]
	ds_read_b128 v[106:109], v66 offset:12304
	s_waitcnt lgkmcnt(15)
	v_pk_fma_f32 v[232:233], v[20:21], v[110:111], v[232:233] op_sel:[0,0,0] op_sel_hi:[0,1,1]
	v_pk_fma_f32 v[234:235], v[20:21], v[112:113], v[234:235] op_sel:[0,0,0] op_sel_hi:[0,1,1]
	ds_read_b128 v[110:113], v66 offset:12320
	s_waitcnt lgkmcnt(15)
	v_pk_fma_f32 v[236:237], v[20:21], v[114:115], v[236:237] op_sel:[0,0,0] op_sel_hi:[0,1,1]
	v_pk_fma_f32 v[238:239], v[20:21], v[116:117], v[238:239] op_sel:[0,0,0] op_sel_hi:[0,1,1]
	ds_read_b128 v[114:117], v66 offset:12336
	s_waitcnt lgkmcnt(15)
	v_pk_fma_f32 v[224:225], v[20:21], v[118:119], v[224:225] op_sel:[1,0,0] op_sel_hi:[1,1,1]
	v_pk_fma_f32 v[226:227], v[20:21], v[120:121], v[226:227] op_sel:[1,0,0] op_sel_hi:[1,1,1]
	ds_read_b128 v[118:121], v66 offset:12544
	s_waitcnt lgkmcnt(15)
	v_pk_fma_f32 v[228:229], v[20:21], v[122:123], v[228:229] op_sel:[1,0,0] op_sel_hi:[1,1,1]
	v_pk_fma_f32 v[230:231], v[20:21], v[124:125], v[230:231] op_sel:[1,0,0] op_sel_hi:[1,1,1]
	ds_read_b128 v[122:125], v66 offset:12560
	s_waitcnt lgkmcnt(15)
	v_pk_fma_f32 v[232:233], v[20:21], v[126:127], v[232:233] op_sel:[1,0,0] op_sel_hi:[1,1,1]
	v_pk_fma_f32 v[234:235], v[20:21], v[128:129], v[234:235] op_sel:[1,0,0] op_sel_hi:[1,1,1]
	ds_read_b128 v[126:129], v66 offset:12576
	s_waitcnt lgkmcnt(15)
	v_pk_fma_f32 v[236:237], v[20:21], v[130:131], v[236:237] op_sel:[1,0,0] op_sel_hi:[1,1,1]
	v_pk_fma_f32 v[238:239], v[20:21], v[132:133], v[238:239] op_sel:[1,0,0] op_sel_hi:[1,1,1]
	ds_read_b128 v[130:133], v66 offset:12592
	s_waitcnt lgkmcnt(15)
	v_pk_fma_f32 v[224:225], v[22:23], v[134:135], v[224:225] op_sel:[0,0,0] op_sel_hi:[0,1,1]
	v_pk_fma_f32 v[226:227], v[22:23], v[136:137], v[226:227] op_sel:[0,0,0] op_sel_hi:[0,1,1]
	ds_read_b128 v[134:137], v66 offset:12800
	s_waitcnt lgkmcnt(15)
	v_pk_fma_f32 v[228:229], v[22:23], v[138:139], v[228:229] op_sel:[0,0,0] op_sel_hi:[0,1,1]
	v_pk_fma_f32 v[230:231], v[22:23], v[140:141], v[230:231] op_sel:[0,0,0] op_sel_hi:[0,1,1]
	ds_read_b128 v[138:141], v66 offset:12816
	s_waitcnt lgkmcnt(15)
	v_pk_fma_f32 v[232:233], v[22:23], v[142:143], v[232:233] op_sel:[0,0,0] op_sel_hi:[0,1,1]
	v_pk_fma_f32 v[234:235], v[22:23], v[144:145], v[234:235] op_sel:[0,0,0] op_sel_hi:[0,1,1]
	ds_read_b128 v[142:145], v66 offset:12832
	s_waitcnt lgkmcnt(15)
	v_pk_fma_f32 v[236:237], v[22:23], v[146:147], v[236:237] op_sel:[0,0,0] op_sel_hi:[0,1,1]
	v_pk_fma_f32 v[238:239], v[22:23], v[148:149], v[238:239] op_sel:[0,0,0] op_sel_hi:[0,1,1]
	ds_read_b128 v[146:149], v66 offset:12848
	s_waitcnt lgkmcnt(15)
	v_pk_fma_f32 v[224:225], v[22:23], v[150:151], v[224:225] op_sel:[1,0,0] op_sel_hi:[1,1,1]
	v_pk_fma_f32 v[226:227], v[22:23], v[152:153], v[226:227] op_sel:[1,0,0] op_sel_hi:[1,1,1]
	ds_read_b128 v[150:153], v66 offset:13056
	s_waitcnt lgkmcnt(15)
	v_pk_fma_f32 v[228:229], v[22:23], v[158:159], v[228:229] op_sel:[1,0,0] op_sel_hi:[1,1,1]
	v_pk_fma_f32 v[230:231], v[22:23], v[160:161], v[230:231] op_sel:[1,0,0] op_sel_hi:[1,1,1]
	ds_read_b128 v[158:161], v66 offset:13072
	s_waitcnt lgkmcnt(15)
	v_pk_fma_f32 v[232:233], v[22:23], v[162:163], v[232:233] op_sel:[1,0,0] op_sel_hi:[1,1,1]
	v_pk_fma_f32 v[234:235], v[22:23], v[164:165], v[234:235] op_sel:[1,0,0] op_sel_hi:[1,1,1]
	ds_read_b128 v[162:165], v66 offset:13088
	s_waitcnt lgkmcnt(15)
	v_pk_fma_f32 v[236:237], v[22:23], v[166:167], v[236:237] op_sel:[1,0,0] op_sel_hi:[1,1,1]
	v_pk_fma_f32 v[238:239], v[22:23], v[168:169], v[238:239] op_sel:[1,0,0] op_sel_hi:[1,1,1]
	ds_read_b128 v[166:169], v66 offset:13104
	s_waitcnt lgkmcnt(15)
	v_pk_fma_f32 v[224:225], v[16:17], v[102:103], v[224:225] op_sel:[0,0,0] op_sel_hi:[0,1,1]
	v_pk_fma_f32 v[226:227], v[16:17], v[104:105], v[226:227] op_sel:[0,0,0] op_sel_hi:[0,1,1]
	ds_read_b128 v[102:105], v66 offset:13312
	s_waitcnt lgkmcnt(15)
	v_pk_fma_f32 v[228:229], v[16:17], v[106:107], v[228:229] op_sel:[0,0,0] op_sel_hi:[0,1,1]
	v_pk_fma_f32 v[230:231], v[16:17], v[108:109], v[230:231] op_sel:[0,0,0] op_sel_hi:[0,1,1]
	ds_read_b128 v[106:109], v66 offset:13328
	s_waitcnt lgkmcnt(15)
; #define LAS __attribute__((address_space(3)))
; __device__ __forceinline__ void phase_prep(const Params& p, LAS unsigned char* lds) {
;     ...
;             for (int c4 = 0; c4 < 16; ++c4) rw[c4] = *(const f32x4*)(row + 4 * c4);
; #pragma unroll
;             for (int c4 = 0; c4 < 16; ++c4)
; #pragma unroll
;                 for (int cc = 0; cc < 4; ++cc) { const float wv = rw[c4][cc]; const LAS f32x4* mp = (const LAS f32x4*)(Mf + (4 * c4 + cc) * 64 + eg * 16);
; #pragma unroll
;                     for (int j4 = 0; j4 < 4; ++j4) { const f32x4 mv = mp[j4]; a[4 * j4 + 0] += wv * mv[0]; a[4 * j4 + 1] += wv * mv[1]; a[4 * j4 + 2] += wv * mv[2]; a[4 * j4 + 3] += wv * mv[3]; } }
	v_pk_fma_f32 v[232:233], v[16:17], v[110:111], v[232:233] op_sel:[0,0,0] op_sel_hi:[0,1,1]
	v_pk_fma_f32 v[234:235], v[16:17], v[112:113], v[234:235] op_sel:[0,0,0] op_sel_hi:[0,1,1]
	ds_read_b128 v[110:113], v66 offset:13344
	s_waitcnt lgkmcnt(15)
	v_pk_fma_f32 v[236:237], v[16:17], v[114:115], v[236:237] op_sel:[0,0,0] op_sel_hi:[0,1,1]
	v_pk_fma_f32 v[238:239], v[16:17], v[116:117], v[238:239] op_sel:[0,0,0] op_sel_hi:[0,1,1]
	ds_read_b128 v[114:117], v66 offset:13360
	s_waitcnt lgkmcnt(15)
	v_pk_fma_f32 v[224:225], v[16:17], v[118:119], v[224:225] op_sel:[1,0,0] op_sel_hi:[1,1,1]
	v_pk_fma_f32 v[226:227], v[16:17], v[120:121], v[226:227] op_sel:[1,0,0] op_sel_hi:[1,1,1]
	ds_read_b128 v[118:121], v66 offset:13568
	s_waitcnt lgkmcnt(15)
	v_pk_fma_f32 v[228:229], v[16:17], v[122:123], v[228:229] op_sel:[1,0,0] op_sel_hi:[1,1,1]
	v_pk_fma_f32 v[230:231], v[16:17], v[124:125], v[230:231] op_sel:[1,0,0] op_sel_hi:[1,1,1]
	ds_read_b128 v[122:125], v66 offset:13584
	s_waitcnt lgkmcnt(15)
	v_pk_fma_f32 v[232:233], v[16:17], v[126:127], v[232:233] op_sel:[1,0,0] op_sel_hi:[1,1,1]
	v_pk_fma_f32 v[234:235], v[16:17], v[128:129], v[234:235] op_sel:[1,0,0] op_sel_hi:[1,1,1]
	ds_read_b128 v[126:129], v66 offset:13600
	s_waitcnt lgkmcnt(15)
	v_pk_fma_f32 v[236:237], v[16:17], v[130:131], v[236:237] op_sel:[1,0,0] op_sel_hi:[1,1,1]
	v_pk_fma_f32 v[238:239], v[16:17], v[132:133], v[238:239] op_sel:[1,0,0] op_sel_hi:[1,1,1]
	ds_read_b128 v[130:133], v66 offset:13616
	s_waitcnt lgkmcnt(15)
	v_pk_fma_f32 v[224:225], v[18:19], v[134:135], v[224:225] op_sel:[0,0,0] op_sel_hi:[0,1,1]
	v_pk_fma_f32 v[226:227], v[18:19], v[136:137], v[226:227] op_sel:[0,0,0] op_sel_hi:[0,1,1]
	ds_read_b128 v[134:137], v66 offset:13824
	s_waitcnt lgkmcnt(15)
	v_pk_fma_f32 v[228:229], v[18:19], v[138:139], v[228:229] op_sel:[0,0,0] op_sel_hi:[0,1,1]
	v_pk_fma_f32 v[230:231], v[18:19], v[140:141], v[230:231] op_sel:[0,0,0] op_sel_hi:[0,1,1]
	ds_read_b128 v[138:141], v66 offset:13840
	s_waitcnt lgkmcnt(15)
	v_pk_fma_f32 v[232:233], v[18:19], v[142:143], v[232:233] op_sel:[0,0,0] op_sel_hi:[0,1,1]
	v_pk_fma_f32 v[234:235], v[18:19], v[144:145], v[234:235] op_sel:[0,0,0] op_sel_hi:[0,1,1]
	ds_read_b128 v[142:145], v66 offset:13856
	s_waitcnt lgkmcnt(15)
	v_pk_fma_f32 v[236:237], v[18:19], v[146:147], v[236:237] op_sel:[0,0,0] op_sel_hi:[0,1,1]
	v_pk_fma_f32 v[238:239], v[18:19], v[148:149], v[238:239] op_sel:[0,0,0] op_sel_hi:[0,1,1]
	ds_read_b128 v[146:149], v66 offset:13872
	s_waitcnt lgkmcnt(15)
	v_pk_fma_f32 v[224:225], v[18:19], v[150:151], v[224:225] op_sel:[1,0,0] op_sel_hi:[1,1,1]
	v_pk_fma_f32 v[226:227], v[18:19], v[152:153], v[226:227] op_sel:[1,0,0] op_sel_hi:[1,1,1]
	ds_read_b128 v[150:153], v66 offset:14080
	s_waitcnt lgkmcnt(15)
	v_pk_fma_f32 v[228:229], v[18:19], v[158:159], v[228:229] op_sel:[1,0,0] op_sel_hi:[1,1,1]
	v_pk_fma_f32 v[230:231], v[18:19], v[160:161], v[230:231] op_sel:[1,0,0] op_sel_hi:[1,1,1]
	ds_read_b128 v[158:161], v66 offset:14096
	s_waitcnt lgkmcnt(15)
	v_pk_fma_f32 v[232:233], v[18:19], v[162:163], v[232:233] op_sel:[1,0,0] op_sel_hi:[1,1,1]
	v_pk_fma_f32 v[234:235], v[18:19], v[164:165], v[234:235] op_sel:[1,0,0] op_sel_hi:[1,1,1]
	ds_read_b128 v[162:165], v66 offset:14112
	s_waitcnt lgkmcnt(15)
	v_pk_fma_f32 v[236:237], v[18:19], v[166:167], v[236:237] op_sel:[1,0,0] op_sel_hi:[1,1,1]
	v_pk_fma_f32 v[238:239], v[18:19], v[168:169], v[238:239] op_sel:[1,0,0] op_sel_hi:[1,1,1]
	ds_read_b128 v[166:169], v66 offset:14128
	s_waitcnt lgkmcnt(15)
	v_pk_fma_f32 v[224:225], v[12:13], v[102:103], v[224:225] op_sel:[0,0,0] op_sel_hi:[0,1,1]
	v_pk_fma_f32 v[226:227], v[12:13], v[104:105], v[226:227] op_sel:[0,0,0] op_sel_hi:[0,1,1]
	ds_read_b128 v[102:105], v66 offset:14336
	s_waitcnt lgkmcnt(15)
	v_pk_fma_f32 v[228:229], v[12:13], v[106:107], v[228:229] op_sel:[0,0,0] op_sel_hi:[0,1,1]
	v_pk_fma_f32 v[230:231], v[12:13], v[108:109], v[230:231] op_sel:[0,0,0] op_sel_hi:[0,1,1]
	ds_read_b128 v[106:109], v66 offset:14352
	s_waitcnt lgkmcnt(15)
	v_pk_fma_f32 v[232:233], v[12:13], v[110:111], v[232:233] op_sel:[0,0,0] op_sel_hi:[0,1,1]
	v_pk_fma_f32 v[234:235], v[12:13], v[112:113], v[234:235] op_sel:[0,0,0] op_sel_hi:[0,1,1]
	ds_read_b128 v[110:113], v66 offset:14368
	s_waitcnt lgkmcnt(15)
	v_pk_fma_f32 v[236:237], v[12:13], v[114:115], v[236:237] op_sel:[0,0,0] op_sel_hi:[0,1,1]
	v_pk_fma_f32 v[238:239], v[12:13], v[116:117], v[238:239] op_sel:[0,0,0] op_sel_hi:[0,1,1]
	ds_read_b128 v[114:117], v66 offset:14384
	s_waitcnt lgkmcnt(15)
	v_pk_fma_f32 v[224:225], v[12:13], v[118:119], v[224:225] op_sel:[1,0,0] op_sel_hi:[1,1,1]
	v_pk_fma_f32 v[226:227], v[12:13], v[120:121], v[226:227] op_sel:[1,0,0] op_sel_hi:[1,1,1]
	ds_read_b128 v[118:121], v66 offset:14592
	s_waitcnt lgkmcnt(15)
	v_pk_fma_f32 v[228:229], v[12:13], v[122:123], v[228:229] op_sel:[1,0,0] op_sel_hi:[1,1,1]
	v_pk_fma_f32 v[230:231], v[12:13], v[124:125], v[230:231] op_sel:[1,0,0] op_sel_hi:[1,1,1]
	ds_read_b128 v[122:125], v66 offset:14608
	s_waitcnt lgkmcnt(15)
	v_pk_fma_f32 v[232:233], v[12:13], v[126:127], v[232:233] op_sel:[1,0,0] op_sel_hi:[1,1,1]
	v_pk_fma_f32 v[234:235], v[12:13], v[128:129], v[234:235] op_sel:[1,0,0] op_sel_hi:[1,1,1]
	ds_read_b128 v[126:129], v66 offset:14624
	s_waitcnt lgkmcnt(15)
	v_pk_fma_f32 v[236:237], v[12:13], v[130:131], v[236:237] op_sel:[1,0,0] op_sel_hi:[1,1,1]
	v_pk_fma_f32 v[238:239], v[12:13], v[132:133], v[238:239] op_sel:[1,0,0] op_sel_hi:[1,1,1]
	ds_read_b128 v[130:133], v66 offset:14640
	s_waitcnt lgkmcnt(15)
	v_pk_fma_f32 v[224:225], v[14:15], v[134:135], v[224:225] op_sel:[0,0,0] op_sel_hi:[0,1,1]
	v_pk_fma_f32 v[226:227], v[14:15], v[136:137], v[226:227] op_sel:[0,0,0] op_sel_hi:[0,1,1]
	ds_read_b128 v[134:137], v66 offset:14848
	s_waitcnt lgkmcnt(15)
; #define LAS __attribute__((address_space(3)))
; __device__ __forceinline__ void phase_prep(const Params& p, LAS unsigned char* lds) {
;     ...
;             for (int c4 = 0; c4 < 16; ++c4) rw[c4] = *(const f32x4*)(row + 4 * c4);
; #pragma unroll
;             for (int c4 = 0; c4 < 16; ++c4)
; #pragma unroll
;                 for (int cc = 0; cc < 4; ++cc) { const float wv = rw[c4][cc]; const LAS f32x4* mp = (const LAS f32x4*)(Mf + (4 * c4 + cc) * 64 + eg * 16);
; #pragma unroll
;                     for (int j4 = 0; j4 < 4; ++j4) { const f32x4 mv = mp[j4]; a[4 * j4 + 0] += wv * mv[0]; a[4 * j4 + 1] += wv * mv[1]; a[4 * j4 + 2] += wv * mv[2]; a[4 * j4 + 3] += wv * mv[3]; } }
	v_pk_fma_f32 v[228:229], v[14:15], v[138:139], v[228:229] op_sel:[0,0,0] op_sel_hi:[0,1,1]
	v_pk_fma_f32 v[230:231], v[14:15], v[140:141], v[230:231] op_sel:[0,0,0] op_sel_hi:[0,1,1]
	ds_read_b128 v[138:141], v66 offset:14864
	s_waitcnt lgkmcnt(15)
	v_pk_fma_f32 v[232:233], v[14:15], v[142:143], v[232:233] op_sel:[0,0,0] op_sel_hi:[0,1,1]
	v_pk_fma_f32 v[234:235], v[14:15], v[144:145], v[234:235] op_sel:[0,0,0] op_sel_hi:[0,1,1]
	ds_read_b128 v[142:145], v66 offset:14880
	s_waitcnt lgkmcnt(15)
	v_pk_fma_f32 v[236:237], v[14:15], v[146:147], v[236:237] op_sel:[0,0,0] op_sel_hi:[0,1,1]
	v_pk_fma_f32 v[238:239], v[14:15], v[148:149], v[238:239] op_sel:[0,0,0] op_sel_hi:[0,1,1]
	ds_read_b128 v[146:149], v66 offset:14896
	s_waitcnt lgkmcnt(15)
	v_pk_fma_f32 v[224:225], v[14:15], v[150:151], v[224:225] op_sel:[1,0,0] op_sel_hi:[1,1,1]
	v_pk_fma_f32 v[226:227], v[14:15], v[152:153], v[226:227] op_sel:[1,0,0] op_sel_hi:[1,1,1]
	ds_read_b128 v[150:153], v66 offset:15104
	s_waitcnt lgkmcnt(15)
	v_pk_fma_f32 v[228:229], v[14:15], v[158:159], v[228:229] op_sel:[1,0,0] op_sel_hi:[1,1,1]
	v_pk_fma_f32 v[230:231], v[14:15], v[160:161], v[230:231] op_sel:[1,0,0] op_sel_hi:[1,1,1]
	ds_read_b128 v[158:161], v66 offset:15120
	s_waitcnt lgkmcnt(15)
	v_pk_fma_f32 v[232:233], v[14:15], v[162:163], v[232:233] op_sel:[1,0,0] op_sel_hi:[1,1,1]
	v_pk_fma_f32 v[234:235], v[14:15], v[164:165], v[234:235] op_sel:[1,0,0] op_sel_hi:[1,1,1]
	ds_read_b128 v[162:165], v66 offset:15136
	s_waitcnt lgkmcnt(15)
	v_pk_fma_f32 v[236:237], v[14:15], v[166:167], v[236:237] op_sel:[1,0,0] op_sel_hi:[1,1,1]
	v_pk_fma_f32 v[238:239], v[14:15], v[168:169], v[238:239] op_sel:[1,0,0] op_sel_hi:[1,1,1]
	ds_read_b128 v[166:169], v66 offset:15152
	s_waitcnt lgkmcnt(15)
	v_pk_fma_f32 v[224:225], v[8:9], v[102:103], v[224:225] op_sel:[0,0,0] op_sel_hi:[0,1,1]
	v_pk_fma_f32 v[226:227], v[8:9], v[104:105], v[226:227] op_sel:[0,0,0] op_sel_hi:[0,1,1]
	ds_read_b128 v[102:105], v66 offset:15360
	s_waitcnt lgkmcnt(15)
	v_pk_fma_f32 v[228:229], v[8:9], v[106:107], v[228:229] op_sel:[0,0,0] op_sel_hi:[0,1,1]
	v_pk_fma_f32 v[230:231], v[8:9], v[108:109], v[230:231] op_sel:[0,0,0] op_sel_hi:[0,1,1]
	ds_read_b128 v[106:109], v66 offset:15376
	s_waitcnt lgkmcnt(15)
	v_pk_fma_f32 v[232:233], v[8:9], v[110:111], v[232:233] op_sel:[0,0,0] op_sel_hi:[0,1,1]
	v_pk_fma_f32 v[234:235], v[8:9], v[112:113], v[234:235] op_sel:[0,0,0] op_sel_hi:[0,1,1]
	ds_read_b128 v[110:113], v66 offset:15392
	s_waitcnt lgkmcnt(15)
	v_pk_fma_f32 v[236:237], v[8:9], v[114:115], v[236:237] op_sel:[0,0,0] op_sel_hi:[0,1,1]
	v_pk_fma_f32 v[238:239], v[8:9], v[116:117], v[238:239] op_sel:[0,0,0] op_sel_hi:[0,1,1]
	ds_read_b128 v[114:117], v66 offset:15408
	s_waitcnt lgkmcnt(15)
	v_pk_fma_f32 v[224:225], v[8:9], v[118:119], v[224:225] op_sel:[1,0,0] op_sel_hi:[1,1,1]
	v_pk_fma_f32 v[226:227], v[8:9], v[120:121], v[226:227] op_sel:[1,0,0] op_sel_hi:[1,1,1]
	ds_read_b128 v[118:121], v66 offset:15616
	s_waitcnt lgkmcnt(15)
	v_pk_fma_f32 v[228:229], v[8:9], v[122:123], v[228:229] op_sel:[1,0,0] op_sel_hi:[1,1,1]
	v_pk_fma_f32 v[230:231], v[8:9], v[124:125], v[230:231] op_sel:[1,0,0] op_sel_hi:[1,1,1]
	ds_read_b128 v[122:125], v66 offset:15632
	s_waitcnt lgkmcnt(15)
	v_pk_fma_f32 v[232:233], v[8:9], v[126:127], v[232:233] op_sel:[1,0,0] op_sel_hi:[1,1,1]
	v_pk_fma_f32 v[234:235], v[8:9], v[128:129], v[234:235] op_sel:[1,0,0] op_sel_hi:[1,1,1]
	ds_read_b128 v[126:129], v66 offset:15648
	s_waitcnt lgkmcnt(15)
	v_pk_fma_f32 v[236:237], v[8:9], v[130:131], v[236:237] op_sel:[1,0,0] op_sel_hi:[1,1,1]
	v_pk_fma_f32 v[238:239], v[8:9], v[132:133], v[238:239] op_sel:[1,0,0] op_sel_hi:[1,1,1]
	ds_read_b128 v[130:133], v66 offset:15664
	s_waitcnt lgkmcnt(15)
	v_pk_fma_f32 v[224:225], v[10:11], v[134:135], v[224:225] op_sel:[0,0,0] op_sel_hi:[0,1,1]
	v_pk_fma_f32 v[226:227], v[10:11], v[136:137], v[226:227] op_sel:[0,0,0] op_sel_hi:[0,1,1]
	ds_read_b128 v[134:137], v66 offset:15872
	s_waitcnt lgkmcnt(15)
	v_pk_fma_f32 v[228:229], v[10:11], v[138:139], v[228:229] op_sel:[0,0,0] op_sel_hi:[0,1,1]
	v_pk_fma_f32 v[230:231], v[10:11], v[140:141], v[230:231] op_sel:[0,0,0] op_sel_hi:[0,1,1]
	ds_read_b128 v[138:141], v66 offset:15888
	s_waitcnt lgkmcnt(15)
	v_pk_fma_f32 v[232:233], v[10:11], v[142:143], v[232:233] op_sel:[0,0,0] op_sel_hi:[0,1,1]
	v_pk_fma_f32 v[234:235], v[10:11], v[144:145], v[234:235] op_sel:[0,0,0] op_sel_hi:[0,1,1]
	ds_read_b128 v[142:145], v66 offset:15904
	s_waitcnt lgkmcnt(15)
	v_pk_fma_f32 v[236:237], v[10:11], v[146:147], v[236:237] op_sel:[0,0,0] op_sel_hi:[0,1,1]
	v_pk_fma_f32 v[238:239], v[10:11], v[148:149], v[238:239] op_sel:[0,0,0] op_sel_hi:[0,1,1]
	ds_read_b128 v[146:149], v66 offset:15920
	s_waitcnt lgkmcnt(15)
	v_pk_fma_f32 v[224:225], v[10:11], v[150:151], v[224:225] op_sel:[1,0,0] op_sel_hi:[1,1,1]
	v_pk_fma_f32 v[226:227], v[10:11], v[152:153], v[226:227] op_sel:[1,0,0] op_sel_hi:[1,1,1]
	ds_read_b128 v[150:153], v66 offset:16128
	s_waitcnt lgkmcnt(15)
	v_pk_fma_f32 v[228:229], v[10:11], v[158:159], v[228:229] op_sel:[1,0,0] op_sel_hi:[1,1,1]
	v_pk_fma_f32 v[230:231], v[10:11], v[160:161], v[230:231] op_sel:[1,0,0] op_sel_hi:[1,1,1]
	ds_read_b128 v[158:161], v66 offset:16144
	s_waitcnt lgkmcnt(15)
	v_pk_fma_f32 v[232:233], v[10:11], v[162:163], v[232:233] op_sel:[1,0,0] op_sel_hi:[1,1,1]
	v_pk_fma_f32 v[234:235], v[10:11], v[164:165], v[234:235] op_sel:[1,0,0] op_sel_hi:[1,1,1]
	ds_read_b128 v[162:165], v66 offset:16160
	s_waitcnt lgkmcnt(15)
	v_pk_fma_f32 v[236:237], v[10:11], v[166:167], v[236:237] op_sel:[1,0,0] op_sel_hi:[1,1,1]
	v_pk_fma_f32 v[238:239], v[10:11], v[168:169], v[238:239] op_sel:[1,0,0] op_sel_hi:[1,1,1]
	ds_read_b128 v[166:169], v66 offset:16176
	s_waitcnt lgkmcnt(15)
; #define LAS __attribute__((address_space(3)))
; __device__ __forceinline__ void phase_prep(const Params& p, LAS unsigned char* lds) {
;     ...
;             for (int c4 = 0; c4 < 16; ++c4) rw[c4] = *(const f32x4*)(row + 4 * c4);
; #pragma unroll
;             for (int c4 = 0; c4 < 16; ++c4)
; #pragma unroll
;                 for (int cc = 0; cc < 4; ++cc) { const float wv = rw[c4][cc]; const LAS f32x4* mp = (const LAS f32x4*)(Mf + (4 * c4 + cc) * 64 + eg * 16);
; #pragma unroll
;                     for (int j4 = 0; j4 < 4; ++j4) { const f32x4 mv = mp[j4]; a[4 * j4 + 0] += wv * mv[0]; a[4 * j4 + 1] += wv * mv[1]; a[4 * j4 + 2] += wv * mv[2]; a[4 * j4 + 3] += wv * mv[3]; } }
	v_pk_fma_f32 v[224:225], v[4:5], v[102:103], v[224:225] op_sel:[0,0,0] op_sel_hi:[0,1,1]
	v_pk_fma_f32 v[226:227], v[4:5], v[104:105], v[226:227] op_sel:[0,0,0] op_sel_hi:[0,1,1]
	ds_read_b128 v[102:105], v66 offset:16384
	s_waitcnt lgkmcnt(15)
	v_pk_fma_f32 v[228:229], v[4:5], v[106:107], v[228:229] op_sel:[0,0,0] op_sel_hi:[0,1,1]
	v_pk_fma_f32 v[230:231], v[4:5], v[108:109], v[230:231] op_sel:[0,0,0] op_sel_hi:[0,1,1]
	ds_read_b128 v[106:109], v66 offset:16400
	s_waitcnt lgkmcnt(15)
	v_pk_fma_f32 v[232:233], v[4:5], v[110:111], v[232:233] op_sel:[0,0,0] op_sel_hi:[0,1,1]
	v_pk_fma_f32 v[234:235], v[4:5], v[112:113], v[234:235] op_sel:[0,0,0] op_sel_hi:[0,1,1]
	ds_read_b128 v[110:113], v66 offset:16416
	s_waitcnt lgkmcnt(15)
	v_pk_fma_f32 v[236:237], v[4:5], v[114:115], v[236:237] op_sel:[0,0,0] op_sel_hi:[0,1,1]
	v_pk_fma_f32 v[238:239], v[4:5], v[116:117], v[238:239] op_sel:[0,0,0] op_sel_hi:[0,1,1]
	ds_read_b128 v[114:117], v66 offset:16432
	s_waitcnt lgkmcnt(15)
	v_pk_fma_f32 v[224:225], v[4:5], v[118:119], v[224:225] op_sel:[1,0,0] op_sel_hi:[1,1,1]
	v_pk_fma_f32 v[226:227], v[4:5], v[120:121], v[226:227] op_sel:[1,0,0] op_sel_hi:[1,1,1]
	ds_read_b128 v[118:121], v66 offset:16640
	s_waitcnt lgkmcnt(15)
	v_pk_fma_f32 v[228:229], v[4:5], v[122:123], v[228:229] op_sel:[1,0,0] op_sel_hi:[1,1,1]
	v_pk_fma_f32 v[230:231], v[4:5], v[124:125], v[230:231] op_sel:[1,0,0] op_sel_hi:[1,1,1]
	ds_read_b128 v[122:125], v66 offset:16656
	s_waitcnt lgkmcnt(15)
	v_pk_fma_f32 v[232:233], v[4:5], v[126:127], v[232:233] op_sel:[1,0,0] op_sel_hi:[1,1,1]
	v_pk_fma_f32 v[234:235], v[4:5], v[128:129], v[234:235] op_sel:[1,0,0] op_sel_hi:[1,1,1]
	ds_read_b128 v[126:129], v66 offset:16672
	s_waitcnt lgkmcnt(15)
	v_pk_fma_f32 v[236:237], v[4:5], v[130:131], v[236:237] op_sel:[1,0,0] op_sel_hi:[1,1,1]
	v_pk_fma_f32 v[238:239], v[4:5], v[132:133], v[238:239] op_sel:[1,0,0] op_sel_hi:[1,1,1]
	ds_read_b128 v[130:133], v66 offset:16688
	s_waitcnt lgkmcnt(15)
	v_pk_fma_f32 v[224:225], v[6:7], v[134:135], v[224:225] op_sel:[0,0,0] op_sel_hi:[0,1,1]
	v_pk_fma_f32 v[226:227], v[6:7], v[136:137], v[226:227] op_sel:[0,0,0] op_sel_hi:[0,1,1]
	ds_read_b128 v[134:137], v66 offset:16896
	s_waitcnt lgkmcnt(15)
	v_pk_fma_f32 v[228:229], v[6:7], v[138:139], v[228:229] op_sel:[0,0,0] op_sel_hi:[0,1,1]
	v_pk_fma_f32 v[230:231], v[6:7], v[140:141], v[230:231] op_sel:[0,0,0] op_sel_hi:[0,1,1]
	ds_read_b128 v[138:141], v66 offset:16912
	s_waitcnt lgkmcnt(15)
	v_pk_fma_f32 v[232:233], v[6:7], v[142:143], v[232:233] op_sel:[0,0,0] op_sel_hi:[0,1,1]
	v_pk_fma_f32 v[234:235], v[6:7], v[144:145], v[234:235] op_sel:[0,0,0] op_sel_hi:[0,1,1]
	ds_read_b128 v[142:145], v66 offset:16928
	s_waitcnt lgkmcnt(15)
	v_pk_fma_f32 v[236:237], v[6:7], v[146:147], v[236:237] op_sel:[0,0,0] op_sel_hi:[0,1,1]
	v_pk_fma_f32 v[238:239], v[6:7], v[148:149], v[238:239] op_sel:[0,0,0] op_sel_hi:[0,1,1]
	ds_read_b128 v[146:149], v66 offset:16944
	s_waitcnt lgkmcnt(15)
	v_pk_fma_f32 v[224:225], v[6:7], v[150:151], v[224:225] op_sel:[1,0,0] op_sel_hi:[1,1,1]
	v_pk_fma_f32 v[226:227], v[6:7], v[152:153], v[226:227] op_sel:[1,0,0] op_sel_hi:[1,1,1]
	ds_read_b128 v[150:153], v66 offset:17152
	s_waitcnt lgkmcnt(15)
	v_pk_fma_f32 v[228:229], v[6:7], v[158:159], v[228:229] op_sel:[1,0,0] op_sel_hi:[1,1,1]
	v_pk_fma_f32 v[230:231], v[6:7], v[160:161], v[230:231] op_sel:[1,0,0] op_sel_hi:[1,1,1]
	ds_read_b128 v[158:161], v66 offset:17168
	s_waitcnt lgkmcnt(15)
	v_pk_fma_f32 v[232:233], v[6:7], v[162:163], v[232:233] op_sel:[1,0,0] op_sel_hi:[1,1,1]
	v_pk_fma_f32 v[234:235], v[6:7], v[164:165], v[234:235] op_sel:[1,0,0] op_sel_hi:[1,1,1]
	ds_read_b128 v[162:165], v66 offset:17184
	s_waitcnt lgkmcnt(15)
	v_pk_fma_f32 v[236:237], v[6:7], v[166:167], v[236:237] op_sel:[1,0,0] op_sel_hi:[1,1,1]
	v_pk_fma_f32 v[238:239], v[6:7], v[168:169], v[238:239] op_sel:[1,0,0] op_sel_hi:[1,1,1]
	ds_read_b128 v[166:169], v66 offset:17200
	s_waitcnt lgkmcnt(15)
	v_pk_fma_f32 v[224:225], v[0:1], v[102:103], v[224:225] op_sel:[0,0,0] op_sel_hi:[0,1,1]
	v_pk_fma_f32 v[226:227], v[0:1], v[104:105], v[226:227] op_sel:[0,0,0] op_sel_hi:[0,1,1]
	s_waitcnt lgkmcnt(14)
	v_pk_fma_f32 v[228:229], v[0:1], v[106:107], v[228:229] op_sel:[0,0,0] op_sel_hi:[0,1,1]
	v_pk_fma_f32 v[230:231], v[0:1], v[108:109], v[230:231] op_sel:[0,0,0] op_sel_hi:[0,1,1]
	s_waitcnt lgkmcnt(13)
	v_pk_fma_f32 v[232:233], v[0:1], v[110:111], v[232:233] op_sel:[0,0,0] op_sel_hi:[0,1,1]
	v_pk_fma_f32 v[234:235], v[0:1], v[112:113], v[234:235] op_sel:[0,0,0] op_sel_hi:[0,1,1]
	s_waitcnt lgkmcnt(12)
	v_pk_fma_f32 v[236:237], v[0:1], v[114:115], v[236:237] op_sel:[0,0,0] op_sel_hi:[0,1,1]
	v_pk_fma_f32 v[238:239], v[0:1], v[116:117], v[238:239] op_sel:[0,0,0] op_sel_hi:[0,1,1]
	s_waitcnt lgkmcnt(11)
	v_pk_fma_f32 v[224:225], v[0:1], v[118:119], v[224:225] op_sel:[1,0,0] op_sel_hi:[1,1,1]
	v_pk_fma_f32 v[226:227], v[0:1], v[120:121], v[226:227] op_sel:[1,0,0] op_sel_hi:[1,1,1]
	s_waitcnt lgkmcnt(10)
	v_pk_fma_f32 v[228:229], v[0:1], v[122:123], v[228:229] op_sel:[1,0,0] op_sel_hi:[1,1,1]
	v_pk_fma_f32 v[230:231], v[0:1], v[124:125], v[230:231] op_sel:[1,0,0] op_sel_hi:[1,1,1]
	s_waitcnt lgkmcnt(9)
; #define LAS __attribute__((address_space(3)))
; __device__ __forceinline__ unsigned f2bf(float f) { unsigned u = __builtin_bit_cast(unsigned, f); return (u + 0x7fffu + ((u >> 16) & 1u)) >> 16; }
; __device__ __forceinline__ void phase_prep(const Params& p, LAS unsigned char* lds) {
;     ...
;                 for (int cc = 0; cc < 4; ++cc) { const float wv = rw[c4][cc]; const LAS f32x4* mp = (const LAS f32x4*)(Mf + (4 * c4 + cc) * 64 + eg * 16);
; #pragma unroll
;                     for (int j4 = 0; j4 < 4; ++j4) { const f32x4 mv = mp[j4]; a[4 * j4 + 0] += wv * mv[0]; a[4 * j4 + 1] += wv * mv[1]; a[4 * j4 + 2] += wv * mv[2]; a[4 * j4 + 3] += wv * mv[3]; } }
;             bf16_t* wt = (bf16_t*)(ws + WS_WF + l * SZ_WF);
; #pragma unroll
;             for (int j = 0; j < 16; ++j) wt[(size_t)(part * 512 + g * 64 + eg * 16 + j) * DM + k] = (bf16_t)f2bf(a[j]);
;             }
	v_pk_fma_f32 v[232:233], v[0:1], v[126:127], v[232:233] op_sel:[1,0,0] op_sel_hi:[1,1,1]
	v_pk_fma_f32 v[234:235], v[0:1], v[128:129], v[234:235] op_sel:[1,0,0] op_sel_hi:[1,1,1]
	s_waitcnt lgkmcnt(8)
	v_pk_fma_f32 v[236:237], v[0:1], v[130:131], v[236:237] op_sel:[1,0,0] op_sel_hi:[1,1,1]
	v_pk_fma_f32 v[238:239], v[0:1], v[132:133], v[238:239] op_sel:[1,0,0] op_sel_hi:[1,1,1]
	s_waitcnt lgkmcnt(7)
	v_pk_fma_f32 v[224:225], v[2:3], v[134:135], v[224:225] op_sel:[0,0,0] op_sel_hi:[0,1,1]
	v_pk_fma_f32 v[226:227], v[2:3], v[136:137], v[226:227] op_sel:[0,0,0] op_sel_hi:[0,1,1]
	s_waitcnt lgkmcnt(6)
	v_pk_fma_f32 v[228:229], v[2:3], v[138:139], v[228:229] op_sel:[0,0,0] op_sel_hi:[0,1,1]
	v_pk_fma_f32 v[230:231], v[2:3], v[140:141], v[230:231] op_sel:[0,0,0] op_sel_hi:[0,1,1]
	s_waitcnt lgkmcnt(5)
	v_pk_fma_f32 v[232:233], v[2:3], v[142:143], v[232:233] op_sel:[0,0,0] op_sel_hi:[0,1,1]
	v_pk_fma_f32 v[234:235], v[2:3], v[144:145], v[234:235] op_sel:[0,0,0] op_sel_hi:[0,1,1]
	s_waitcnt lgkmcnt(4)
	v_pk_fma_f32 v[236:237], v[2:3], v[146:147], v[236:237] op_sel:[0,0,0] op_sel_hi:[0,1,1]
	v_pk_fma_f32 v[238:239], v[2:3], v[148:149], v[238:239] op_sel:[0,0,0] op_sel_hi:[0,1,1]
	s_waitcnt lgkmcnt(3)
	v_pk_fma_f32 v[224:225], v[2:3], v[150:151], v[224:225] op_sel:[1,0,0] op_sel_hi:[1,1,1]
	v_pk_fma_f32 v[226:227], v[2:3], v[152:153], v[226:227] op_sel:[1,0,0] op_sel_hi:[1,1,1]
	s_waitcnt lgkmcnt(2)
	v_pk_fma_f32 v[228:229], v[2:3], v[158:159], v[228:229] op_sel:[1,0,0] op_sel_hi:[1,1,1]
	v_pk_fma_f32 v[230:231], v[2:3], v[160:161], v[230:231] op_sel:[1,0,0] op_sel_hi:[1,1,1]
	s_waitcnt lgkmcnt(1)
	v_pk_fma_f32 v[232:233], v[2:3], v[162:163], v[232:233] op_sel:[1,0,0] op_sel_hi:[1,1,1]
	v_pk_fma_f32 v[234:235], v[2:3], v[164:165], v[234:235] op_sel:[1,0,0] op_sel_hi:[1,1,1]
	s_waitcnt lgkmcnt(0)
	v_pk_fma_f32 v[236:237], v[2:3], v[166:167], v[236:237] op_sel:[1,0,0] op_sel_hi:[1,1,1]
	v_pk_fma_f32 v[238:239], v[2:3], v[168:169], v[238:239] op_sel:[1,0,0] op_sel_hi:[1,1,1]
	v_mov_b32_e32 v84, v224
	v_mov_b32_e32 v83, v225
	v_mov_b32_e32 v82, v226
	v_mov_b32_e32 v81, v227
	v_mov_b32_e32 v80, v228
	v_mov_b32_e32 v79, v229
	v_mov_b32_e32 v78, v230
	v_mov_b32_e32 v77, v231
	v_mov_b32_e32 v76, v232
	v_mov_b32_e32 v75, v233
	v_mov_b32_e32 v74, v234
	v_mov_b32_e32 v73, v235
	v_mov_b32_e32 v72, v236
	v_mov_b32_e32 v71, v237
	v_mov_b32_e32 v70, v238
	v_mov_b32_e32 v69, v239
	v_bfe_u32 v0, v84, 16, 1
	v_add3_u32 v0, v84, v0, s34
	v_lshl_add_u64 v[2:3], v[60:61], 0, s[0:1]
	v_add_co_u32_e32 v4, vcc, s2, v2
	s_mov_b32 s2, 0x4003000
	s_nop 0
	v_addc_co_u32_e32 v5, vcc, 0, v3, vcc
	global_store_short_d16_hi v[4:5], v0, off offset:-4096
	v_bfe_u32 v0, v83, 16, 1
	v_add3_u32 v0, v83, v0, s34
	global_store_short_d16_hi v[4:5], v0, off
	v_bfe_u32 v0, v82, 16, 1
	v_add3_u32 v4, v82, v0, s34
	v_add_co_u32_e32 v0, vcc, s2, v2
	s_mov_b32 s2, 0x4005000
	s_nop 0
	v_addc_co_u32_e32 v1, vcc, 0, v3, vcc
	global_store_short_d16_hi v[0:1], v4, off offset:-4096
	v_bfe_u32 v4, v81, 16, 1
	v_add3_u32 v4, v81, v4, s34
	global_store_short_d16_hi v[0:1], v4, off
	v_bfe_u32 v0, v80, 16, 1
	v_add3_u32 v4, v80, v0, s34
	v_add_co_u32_e32 v0, vcc, s2, v2
	s_mov_b32 s2, 0x4007000
	s_nop 0
	v_addc_co_u32_e32 v1, vcc, 0, v3, vcc
	global_store_short_d16_hi v[0:1], v4, off offset:-4096
	v_bfe_u32 v4, v79, 16, 1
	v_add3_u32 v4, v79, v4, s34
	global_store_short_d16_hi v[0:1], v4, off
	v_bfe_u32 v0, v78, 16, 1
	v_add3_u32 v4, v78, v0, s34
	v_add_co_u32_e32 v0, vcc, s2, v2
	s_mov_b32 s2, 0x4009000
	s_nop 0
	v_addc_co_u32_e32 v1, vcc, 0, v3, vcc
	global_store_short_d16_hi v[0:1], v4, off offset:-4096
	v_bfe_u32 v4, v77, 16, 1
	v_add3_u32 v4, v77, v4, s34
	global_store_short_d16_hi v[0:1], v4, off
	v_bfe_u32 v0, v76, 16, 1
	v_add3_u32 v4, v76, v0, s34
	v_add_co_u32_e32 v0, vcc, s2, v2
	s_mov_b32 s2, 0x400b000
	s_nop 0
	v_addc_co_u32_e32 v1, vcc, 0, v3, vcc
	global_store_short_d16_hi v[0:1], v4, off offset:-4096
	v_bfe_u32 v4, v75, 16, 1
	v_add3_u32 v4, v75, v4, s34
	global_store_short_d16_hi v[0:1], v4, off
	v_bfe_u32 v0, v74, 16, 1
	v_add3_u32 v4, v74, v0, s34
	v_add_co_u32_e32 v0, vcc, s2, v2
	s_mov_b32 s2, 0x400d000
	s_nop 0
	v_addc_co_u32_e32 v1, vcc, 0, v3, vcc
	global_store_short_d16_hi v[0:1], v4, off offset:-4096
	v_bfe_u32 v4, v73, 16, 1
	v_add3_u32 v4, v73, v4, s34
	global_store_short_d16_hi v[0:1], v4, off
	v_bfe_u32 v0, v72, 16, 1
	v_add3_u32 v4, v72, v0, s34
	v_add_co_u32_e32 v0, vcc, s2, v2
	s_mov_b32 s2, 0x400e000
	s_nop 0
	v_addc_co_u32_e32 v1, vcc, 0, v3, vcc
	global_store_short_d16_hi v[0:1], v4, off offset:-4096
	v_bfe_u32 v4, v71, 16, 1
	v_add3_u32 v4, v71, v4, s34
	global_store_short_d16_hi v[0:1], v4, off
	v_bfe_u32 v0, v70, 16, 1
	v_add3_u32 v4, v70, v0, s34
	v_add_co_u32_e32 v0, vcc, s2, v2
	s_add_u32 s0, s0, 0x100
	s_nop 0
	v_addc_co_u32_e32 v1, vcc, 0, v3, vcc
	global_store_short_d16_hi v[0:1], v4, off
	v_bfe_u32 v0, v69, 16, 1
	v_add3_u32 v4, v69, v0, s34
	v_add_co_u32_e32 v0, vcc, 0x400f000, v2
	s_addc_u32 s1, s1, 0
	s_mov_b64 s[2:3], 0x240000
	v_addc_co_u32_e32 v1, vcc, 0, v3, vcc
	v_lshl_add_u64 v[62:63], v[62:63], 0, s[2:3]
	s_cmpk_eq_i32 s0, 0x400
	global_store_short_d16_hi v[0:1], v4, off
	s_cbranch_scc0 .LBB0_581
	s_add_i32 s10, s10, s15
	s_add_i32 s8, s8, s9
	s_cmpk_gt_i32 s10, 0xff
	s_cbranch_scc0 .LBB0_575
